# K-loop MFMA order variant 32_chain_a (+ load segments without VALU copies)
# speedup vs baseline: 1.0191x; 1.0191x over previous
; #define PG8_STAGE(bufoff, gbase, voff) do { const char* gb_ = (const char*)(gbase); asm volatile("" : "+s"(gb_)); _Pragma("unroll") for (int _i = 0; _i < 2; ++_i) { unsigned vo_ = (voff)[_i]; asm volatile("" : "+v"(vo_));        \
;         __builtin_amdgcn_global_load_lds((const unsigned*)(gb_ + vo_), (PG8_LAS unsigned*)(lds + (bufoff) + ldsw + _i * 8192), 16, 0, 0); } } while (0)
; #define PG8_LDA(dst, b, h) do { _Pragma("unroll") for (int m = 0; m < 4; ++m) _Pragma("unroll") for (int k = 0; k < 2; ++k) dst[m][k] = *(const PG8_LAS bf16x8*)(lds + PG8_SA(b, h) + aoff + m * 2048 + k * 1024); } while (0)
; #define PG8_LDB(dst, b, h) do { _Pragma("unroll") for (int n = 0; n < 2; ++n) _Pragma("unroll") for (int k = 0; k < 2; ++k) dst[n][k] = *(const PG8_LAS bf16x8*)(lds + PG8_SB(b, h) + boff + n * 2048 + k * 1024); } while (0)
; #define PG8_MMA(ai, bj, At, Bt) do { __builtin_amdgcn_s_setprio(1); _Pragma("unroll") for (int m = 0; m < 4; ++m) _Pragma("unroll") for (int n = 0; n < 2; ++n) _Pragma("unroll") for (int k = 0; k < 2; ++k) \
;         acc[ai][bj][m][n] = __builtin_amdgcn_mfma_f32_16x16x32_bf16(Bt[n][k], At[m][k], acc[ai][bj][m][n], 0, 0, 0); __builtin_amdgcn_s_setprio(0); } while (0)
; #define PG8_WAIT_V(n) asm volatile("s_waitcnt vmcnt(" #n ")" ::: "memory")
; template <class Epi, class Sched, bool ALIGN_EPI = false, bool SP2 = false>
; __device__ __forceinline__ void gemm_phase(PG8_LAS unsigned char* lds, const Gemm g, const Sched& S, const Epi& E) {
;     ...
;             const bool last = (t == nt - 2);
;             const char* a1 = cA + (size_t)(t + 1) * kstep;
;             const char* a2 = last ? nA : cA + (size_t)(t + 2) * kstep; const char* b2 = last ? nB : cB + (size_t)(t + 2) * kstep;
;             const char* a3 = a2 + kstep; const char* b3 = b2 + kstep;
;             if (last && has_next) S.a_ready(nxt);
;             if constexpr (SP2) {
;             PG8_LDB(B0, 0, 0); PG8_LDB(B1, 0, 1); PG8_SCHED; PG8_LDA(At, 0, 0); PG8_STAGE(PG8_SA(1, 1), a1 + hstep, voffA);
;             PG8_WAIT_V(8); PG8_WAIT_L(0); PG8_BAR; PG8_MMA(0, 0, At, B0); PG8_MMA(0, 1, At, B1); PG8_BAR; PG8_SCHED;
;             PG8_LDA(At, 0, 1); PG8_STAGE(PG8_SB(0, 0), b2, voffB); PG8_STAGE(PG8_SB(0, 1), b2 + hstep, voffB); PG8_STAGE(PG8_SA(0, 0), a2, voffA);
;             PG8_WAIT_V(8); PG8_WAIT_L(0); PG8_BAR; PG8_MMA(1, 0, At, B0); PG8_MMA(1, 1, At, B1); PG8_BAR; PG8_SCHED;
.LBB0_232:
	s_add_u32 s2, s0, 0x100
	s_addc_u32 s3, s1, 0
	s_cmp_eq_u32 s30, 28
	s_cselect_b32 s10, s25, s2
	s_cselect_b32 s11, s24, s3
	s_cselect_b32 s8, s27, s28
	s_cselect_b32 s9, s26, s29
	s_add_u32 s6, s10, 0x80
	s_addc_u32 s7, s11, 0
	s_add_i32 s31, 0, 0x10000
	s_add_i32 s33, 0, 0x14000
	ds_read_b128 v[66:69], v244
	ds_read_b128 v[70:73], v244 offset:1024
	ds_read_b128 v[74:77], v244 offset:2048
	ds_read_b128 v[78:81], v244 offset:3072
	ds_read_b128 v[146:149], v244 offset:16384
	ds_read_b128 v[150:153], v244 offset:17408
	ds_read_b128 v[154:157], v244 offset:18432
	ds_read_b128 v[158:161], v244 offset:19456
	s_add_u32 s0, s0, 0x80080
	s_addc_u32 s1, s1, 0
	ds_read_b128 v[178:181], v223
	ds_read_b128 v[182:185], v223 offset:1024
	ds_read_b128 v[192:195], v223 offset:2048
	ds_read_b128 v[196:199], v223 offset:3072
	ds_read_b128 v[200:203], v223 offset:4096
	ds_read_b128 v[204:207], v223 offset:5120
	ds_read_b128 v[208:211], v223 offset:6144
	ds_read_b128 v[212:215], v223 offset:7168
	s_add_i32 m0, s13, 0xc000
	s_nop 0
	global_load_lds_dwordx4 v1, s[0:1]
	s_add_i32 m0, s13, 0xe000
	s_nop 0
	global_load_lds_dwordx4 v191, s[0:1]
	s_waitcnt vmcnt(8)
	s_waitcnt lgkmcnt(0)
	s_barrier
	s_setprio 1
	s_waitcnt lgkmcnt(0)
	v_mfma_f32_16x16x32_bf16 v[142:145], v[66:69], v[178:181], v[142:145]
	v_mfma_f32_16x16x32_bf16 v[142:145], v[70:73], v[182:185], v[142:145]
	v_mfma_f32_16x16x32_bf16 v[134:137], v[66:69], v[192:195], v[134:137]
	v_mfma_f32_16x16x32_bf16 v[134:137], v[70:73], v[196:199], v[134:137]
	v_mfma_f32_16x16x32_bf16 v[126:129], v[66:69], v[200:203], v[126:129]
	v_mfma_f32_16x16x32_bf16 v[126:129], v[70:73], v[204:207], v[126:129]
	v_mfma_f32_16x16x32_bf16 v[118:121], v[66:69], v[208:211], v[118:121]
	v_mfma_f32_16x16x32_bf16 v[118:121], v[70:73], v[212:215], v[118:121]
	v_mfma_f32_16x16x32_bf16 v[138:141], v[74:77], v[178:181], v[138:141]
	v_mfma_f32_16x16x32_bf16 v[138:141], v[78:81], v[182:185], v[138:141]
	v_mfma_f32_16x16x32_bf16 v[130:133], v[74:77], v[192:195], v[130:133]
	v_mfma_f32_16x16x32_bf16 v[130:133], v[78:81], v[196:199], v[130:133]
	v_mfma_f32_16x16x32_bf16 v[122:125], v[74:77], v[200:203], v[122:125]
	v_mfma_f32_16x16x32_bf16 v[122:125], v[78:81], v[204:207], v[122:125]
	v_mfma_f32_16x16x32_bf16 v[114:117], v[74:77], v[208:211], v[114:117]
	v_mfma_f32_16x16x32_bf16 v[114:117], v[78:81], v[212:215], v[114:117]
	v_mfma_f32_16x16x32_bf16 v[62:65], v[146:149], v[178:181], v[62:65]
	v_mfma_f32_16x16x32_bf16 v[62:65], v[150:153], v[182:185], v[62:65]
	v_mfma_f32_16x16x32_bf16 v[54:57], v[146:149], v[192:195], v[54:57]
	v_mfma_f32_16x16x32_bf16 v[54:57], v[150:153], v[196:199], v[54:57]
	v_mfma_f32_16x16x32_bf16 v[46:49], v[146:149], v[200:203], v[46:49]
	v_mfma_f32_16x16x32_bf16 v[46:49], v[150:153], v[204:207], v[46:49]
	v_mfma_f32_16x16x32_bf16 v[38:41], v[146:149], v[208:211], v[38:41]
	v_mfma_f32_16x16x32_bf16 v[38:41], v[150:153], v[212:215], v[38:41]
	v_mfma_f32_16x16x32_bf16 v[58:61], v[154:157], v[178:181], v[58:61]
	v_mfma_f32_16x16x32_bf16 v[58:61], v[158:161], v[182:185], v[58:61]
	v_mfma_f32_16x16x32_bf16 v[50:53], v[154:157], v[192:195], v[50:53]
	v_mfma_f32_16x16x32_bf16 v[50:53], v[158:161], v[196:199], v[50:53]
	v_mfma_f32_16x16x32_bf16 v[42:45], v[154:157], v[200:203], v[42:45]
	v_mfma_f32_16x16x32_bf16 v[42:45], v[158:161], v[204:207], v[42:45]
	v_mfma_f32_16x16x32_bf16 v[34:37], v[154:157], v[208:211], v[34:37]
	v_mfma_f32_16x16x32_bf16 v[34:37], v[158:161], v[212:215], v[34:37]
	s_setprio 0
	s_barrier
	s_mov_b64 s[0:1], s[8:9]
	s_add_i32 s31, s31, s12
	ds_read_b128 v[178:181], v223 offset:16384
	ds_read_b128 v[182:185], v223 offset:17408
	ds_read_b128 v[192:195], v223 offset:18432
	ds_read_b128 v[196:199], v223 offset:19456
	ds_read_b128 v[200:203], v223 offset:20480
	ds_read_b128 v[204:207], v223 offset:21504
	ds_read_b128 v[208:211], v223 offset:22528
	ds_read_b128 v[212:215], v223 offset:23552
	s_mov_b32 m0, s31
	s_nop 0
	global_load_lds_dwordx4 v189, s[0:1]
	s_add_i32 m0, s31, 0x2000
	s_nop 0
	global_load_lds_dwordx4 v219, s[0:1]
	s_add_u32 s0, s8, 0x80000
	s_addc_u32 s1, s9, 0
	s_add_i32 s31, s33, s12
	s_mov_b32 m0, s31
	s_nop 0
	global_load_lds_dwordx4 v189, s[0:1]
	s_add_i32 m0, s31, 0x2000
	s_nop 0
	global_load_lds_dwordx4 v219, s[0:1]
	s_mov_b64 s[0:1], s[10:11]
	s_mov_b32 m0, s13
	s_nop 0
	global_load_lds_dwordx4 v1, s[0:1]
	s_mov_b32 m0, s14
	s_nop 0
	global_load_lds_dwordx4 v191, s[0:1]
	s_waitcnt vmcnt(8)
	s_waitcnt lgkmcnt(0)
	s_barrier
	s_setprio 1
	s_waitcnt lgkmcnt(0)
	v_mfma_f32_16x16x32_bf16 v[110:113], v[66:69], v[178:181], v[110:113]
	v_mfma_f32_16x16x32_bf16 v[110:113], v[70:73], v[182:185], v[110:113]
	v_mfma_f32_16x16x32_bf16 v[102:105], v[66:69], v[192:195], v[102:105]
	v_mfma_f32_16x16x32_bf16 v[102:105], v[70:73], v[196:199], v[102:105]
	v_mfma_f32_16x16x32_bf16 v[94:97], v[66:69], v[200:203], v[94:97]
	v_mfma_f32_16x16x32_bf16 v[94:97], v[70:73], v[204:207], v[94:97]
	v_mfma_f32_16x16x32_bf16 v[66:69], v[66:69], v[208:211], v[86:89]
	v_mfma_f32_16x16x32_bf16 v[66:69], v[70:73], v[212:215], v[66:69]
	v_mfma_f32_16x16x32_bf16 v[106:109], v[74:77], v[178:181], v[106:109]
	v_mfma_f32_16x16x32_bf16 v[106:109], v[78:81], v[182:185], v[106:109]
	v_mfma_f32_16x16x32_bf16 v[98:101], v[74:77], v[192:195], v[98:101]
	v_mfma_f32_16x16x32_bf16 v[98:101], v[78:81], v[196:199], v[98:101]
	v_mfma_f32_16x16x32_bf16 v[90:93], v[74:77], v[200:203], v[90:93]
	v_mfma_f32_16x16x32_bf16 v[90:93], v[78:81], v[204:207], v[90:93]
	v_mfma_f32_16x16x32_bf16 v[70:73], v[74:77], v[208:211], v[82:85]
	v_mfma_f32_16x16x32_bf16 v[70:73], v[78:81], v[212:215], v[70:73]
	v_mfma_f32_16x16x32_bf16 v[30:33], v[146:149], v[178:181], v[30:33]
	v_mfma_f32_16x16x32_bf16 v[30:33], v[150:153], v[182:185], v[30:33]
	v_mfma_f32_16x16x32_bf16 v[22:25], v[146:149], v[192:195], v[22:25]
	v_mfma_f32_16x16x32_bf16 v[22:25], v[150:153], v[196:199], v[22:25]
	v_mfma_f32_16x16x32_bf16 v[14:17], v[146:149], v[200:203], v[14:17]
	v_mfma_f32_16x16x32_bf16 v[14:17], v[150:153], v[204:207], v[14:17]
	v_mfma_f32_16x16x32_bf16 v[6:9], v[146:149], v[208:211], v[6:9]
	v_mfma_f32_16x16x32_bf16 v[6:9], v[150:153], v[212:215], v[6:9]
	v_mfma_f32_16x16x32_bf16 v[26:29], v[154:157], v[178:181], v[26:29]
	v_mfma_f32_16x16x32_bf16 v[26:29], v[158:161], v[182:185], v[26:29]
	v_mfma_f32_16x16x32_bf16 v[18:21], v[154:157], v[192:195], v[18:21]
	v_mfma_f32_16x16x32_bf16 v[18:21], v[158:161], v[196:199], v[18:21]
	v_mfma_f32_16x16x32_bf16 v[10:13], v[154:157], v[200:203], v[10:13]
	v_mfma_f32_16x16x32_bf16 v[10:13], v[158:161], v[204:207], v[10:13]
	v_mfma_f32_16x16x32_bf16 v[2:5], v[154:157], v[208:211], v[2:5]
	v_mfma_f32_16x16x32_bf16 v[2:5], v[158:161], v[212:215], v[2:5]
	s_setprio 0
	s_barrier
; #define PG8_STAGE(bufoff, gbase, voff) do { const char* gb_ = (const char*)(gbase); asm volatile("" : "+s"(gb_)); _Pragma("unroll") for (int _i = 0; _i < 2; ++_i) { unsigned vo_ = (voff)[_i]; asm volatile("" : "+v"(vo_));        \
;         __builtin_amdgcn_global_load_lds((const unsigned*)(gb_ + vo_), (PG8_LAS unsigned*)(lds + (bufoff) + ldsw + _i * 8192), 16, 0, 0); } } while (0)
; #define PG8_LDA(dst, b, h) do { _Pragma("unroll") for (int m = 0; m < 4; ++m) _Pragma("unroll") for (int k = 0; k < 2; ++k) dst[m][k] = *(const PG8_LAS bf16x8*)(lds + PG8_SA(b, h) + aoff + m * 2048 + k * 1024); } while (0)
; #define PG8_LDB(dst, b, h) do { _Pragma("unroll") for (int n = 0; n < 2; ++n) _Pragma("unroll") for (int k = 0; k < 2; ++k) dst[n][k] = *(const PG8_LAS bf16x8*)(lds + PG8_SB(b, h) + boff + n * 2048 + k * 1024); } while (0)
; #define PG8_MMA(ai, bj, At, Bt) do { __builtin_amdgcn_s_setprio(1); _Pragma("unroll") for (int m = 0; m < 4; ++m) _Pragma("unroll") for (int n = 0; n < 2; ++n) _Pragma("unroll") for (int k = 0; k < 2; ++k) \
;         acc[ai][bj][m][n] = __builtin_amdgcn_mfma_f32_16x16x32_bf16(Bt[n][k], At[m][k], acc[ai][bj][m][n], 0, 0, 0); __builtin_amdgcn_s_setprio(0); } while (0)
; #define PG8_WAIT_V(n) asm volatile("s_waitcnt vmcnt(" #n ")" ::: "memory")
; #define PG8_WAIT_L(n) asm volatile("s_waitcnt lgkmcnt(" #n ")" ::: "memory")
; #define PG8_BAR __builtin_amdgcn_s_barrier()
; #define PG8_SCHED __builtin_amdgcn_sched_barrier(0)
; template <class Epi, class Sched, bool ALIGN_EPI = false, bool SP2 = false>
; __device__ __forceinline__ void gemm_phase(PG8_LAS unsigned char* lds, const Gemm g, const Sched& S, const Epi& E) {
;     ...
;             PG8_LDB(B0, 1, 0); PG8_LDB(B1, 1, 1); PG8_SCHED; PG8_LDA(At, 1, 0); PG8_STAGE(PG8_SA(0, 1), a2 + hstep, voffA);
;             PG8_WAIT_V(8); PG8_WAIT_L(0); PG8_BAR; PG8_MMA(0, 0, At, B0); PG8_MMA(0, 1, At, B1); PG8_BAR; PG8_SCHED;
;             PG8_LDA(At, 1, 1); PG8_STAGE(PG8_SB(1, 0), b3, voffB); PG8_STAGE(PG8_SB(1, 1), b3 + hstep, voffB); PG8_STAGE(PG8_SA(1, 0), a3, voffA);
;             PG8_WAIT_V(8); PG8_WAIT_L(0); PG8_BAR; PG8_MMA(1, 0, At, B0); PG8_MMA(1, 1, At, B1); PG8_BAR; PG8_SCHED;
	s_add_i32 s31, 0, 0x18000
	s_add_i32 s33, 0, 0x1c000
	ds_read_b128 v[74:77], v244 offset:32768
	ds_read_b128 v[78:81], v244 offset:33792
	ds_read_b128 v[82:85], v244 offset:34816
	ds_read_b128 v[146:149], v244 offset:35840
	ds_read_b128 v[150:153], v244 offset:49152
	ds_read_b128 v[154:157], v244 offset:50176
	ds_read_b128 v[158:161], v244 offset:51200
	ds_read_b128 v[178:181], v244 offset:52224
	s_add_u32 s0, s10, 0x80000
	s_addc_u32 s1, s11, 0
	s_mov_b32 m0, s15
	ds_read_b128 v[86:89], v223 offset:32768
	ds_read_b128 v[182:185], v223 offset:33792
	ds_read_b128 v[192:195], v223 offset:34816
	ds_read_b128 v[196:199], v223 offset:35840
	ds_read_b128 v[200:203], v223 offset:36864
	ds_read_b128 v[204:207], v223 offset:37888
	ds_read_b128 v[208:211], v223 offset:38912
	ds_read_b128 v[212:215], v223 offset:39936
	s_nop 0
	global_load_lds_dwordx4 v1, s[0:1]
	s_mov_b32 m0, s16
	s_nop 0
	global_load_lds_dwordx4 v191, s[0:1]
	s_waitcnt vmcnt(8)
	s_waitcnt lgkmcnt(0)
	s_barrier
	s_setprio 1
	s_waitcnt lgkmcnt(0)
	v_mfma_f32_16x16x32_bf16 v[142:145], v[74:77], v[86:89], v[142:145]
	v_mfma_f32_16x16x32_bf16 v[142:145], v[78:81], v[182:185], v[142:145]
	v_mfma_f32_16x16x32_bf16 v[134:137], v[74:77], v[192:195], v[134:137]
	v_mfma_f32_16x16x32_bf16 v[134:137], v[78:81], v[196:199], v[134:137]
	v_mfma_f32_16x16x32_bf16 v[126:129], v[74:77], v[200:203], v[126:129]
	v_mfma_f32_16x16x32_bf16 v[126:129], v[78:81], v[204:207], v[126:129]
	v_mfma_f32_16x16x32_bf16 v[118:121], v[74:77], v[208:211], v[118:121]
	v_mfma_f32_16x16x32_bf16 v[118:121], v[78:81], v[212:215], v[118:121]
	v_mfma_f32_16x16x32_bf16 v[138:141], v[82:85], v[86:89], v[138:141]
	v_mfma_f32_16x16x32_bf16 v[138:141], v[146:149], v[182:185], v[138:141]
	v_mfma_f32_16x16x32_bf16 v[130:133], v[82:85], v[192:195], v[130:133]
	v_mfma_f32_16x16x32_bf16 v[130:133], v[146:149], v[196:199], v[130:133]
	v_mfma_f32_16x16x32_bf16 v[122:125], v[82:85], v[200:203], v[122:125]
	v_mfma_f32_16x16x32_bf16 v[122:125], v[146:149], v[204:207], v[122:125]
	v_mfma_f32_16x16x32_bf16 v[114:117], v[82:85], v[208:211], v[114:117]
	v_mfma_f32_16x16x32_bf16 v[114:117], v[146:149], v[212:215], v[114:117]
	v_mfma_f32_16x16x32_bf16 v[62:65], v[150:153], v[86:89], v[62:65]
	v_mfma_f32_16x16x32_bf16 v[62:65], v[154:157], v[182:185], v[62:65]
	v_mfma_f32_16x16x32_bf16 v[54:57], v[150:153], v[192:195], v[54:57]
	v_mfma_f32_16x16x32_bf16 v[54:57], v[154:157], v[196:199], v[54:57]
	v_mfma_f32_16x16x32_bf16 v[46:49], v[150:153], v[200:203], v[46:49]
	v_mfma_f32_16x16x32_bf16 v[46:49], v[154:157], v[204:207], v[46:49]
	v_mfma_f32_16x16x32_bf16 v[38:41], v[150:153], v[208:211], v[38:41]
	v_mfma_f32_16x16x32_bf16 v[38:41], v[154:157], v[212:215], v[38:41]
	v_mfma_f32_16x16x32_bf16 v[58:61], v[158:161], v[86:89], v[58:61]
	v_mfma_f32_16x16x32_bf16 v[58:61], v[178:181], v[182:185], v[58:61]
	v_mfma_f32_16x16x32_bf16 v[50:53], v[158:161], v[192:195], v[50:53]
	v_mfma_f32_16x16x32_bf16 v[50:53], v[178:181], v[196:199], v[50:53]
	v_mfma_f32_16x16x32_bf16 v[42:45], v[158:161], v[200:203], v[42:45]
	v_mfma_f32_16x16x32_bf16 v[42:45], v[178:181], v[204:207], v[42:45]
	v_mfma_f32_16x16x32_bf16 v[34:37], v[158:161], v[208:211], v[34:37]
	v_mfma_f32_16x16x32_bf16 v[34:37], v[178:181], v[212:215], v[34:37]
	s_setprio 0
	s_barrier
	s_add_u32 s0, s8, 0x80
	s_addc_u32 s1, s9, 0
	s_add_i32 s10, s31, s12
	ds_read_b128 v[182:185], v223 offset:49152
	ds_read_b128 v[192:195], v223 offset:50176
	ds_read_b128 v[196:199], v223 offset:51200
	ds_read_b128 v[200:203], v223 offset:52224
	ds_read_b128 v[204:207], v223 offset:53248
	ds_read_b128 v[208:211], v223 offset:54272
	ds_read_b128 v[212:215], v223 offset:55296
	ds_read_b128 v[224:227], v223 offset:56320
	s_mov_b32 m0, s10
	s_nop 0
	global_load_lds_dwordx4 v189, s[0:1]
	s_add_i32 m0, s10, 0x2000
	s_nop 0
	global_load_lds_dwordx4 v219, s[0:1]
	s_add_u32 s0, s8, 0x80080
	s_addc_u32 s1, s9, 0
	s_add_i32 s8, s33, s12
	s_mov_b32 m0, s8
	s_nop 0
	global_load_lds_dwordx4 v189, s[0:1]
	s_add_i32 m0, s8, 0x2000
	s_nop 0
	global_load_lds_dwordx4 v219, s[0:1]
	s_mov_b32 m0, s19
	s_nop 0
	global_load_lds_dwordx4 v1, s[6:7]
	s_mov_b32 m0, s20
	s_nop 0
	global_load_lds_dwordx4 v191, s[6:7]
	s_waitcnt vmcnt(8)
	s_waitcnt lgkmcnt(0)
	s_barrier
	s_setprio 1
	s_waitcnt lgkmcnt(0)
	v_mfma_f32_16x16x32_bf16 v[86:89], v[74:77], v[182:185], v[110:113]
	v_mfma_f32_16x16x32_bf16 v[110:113], v[78:81], v[192:195], v[86:89]
	v_mfma_f32_16x16x32_bf16 v[66:69], v[74:77], v[212:215], v[66:69]
	v_mfma_f32_16x16x32_bf16 v[86:89], v[82:85], v[182:185], v[106:109]
	v_mfma_f32_16x16x32_bf16 v[106:109], v[146:149], v[192:195], v[86:89]
	v_mfma_f32_16x16x32_bf16 v[86:89], v[74:77], v[196:199], v[102:105]
	v_mfma_f32_16x16x32_bf16 v[102:105], v[78:81], v[200:203], v[86:89]
	v_mfma_f32_16x16x32_bf16 v[86:89], v[82:85], v[196:199], v[98:101]
	v_mfma_f32_16x16x32_bf16 v[98:101], v[146:149], v[200:203], v[86:89]
	v_mfma_f32_16x16x32_bf16 v[86:89], v[74:77], v[204:207], v[94:97]
	v_mfma_f32_16x16x32_bf16 v[94:97], v[78:81], v[208:211], v[86:89]
	v_mfma_f32_16x16x32_bf16 v[86:89], v[82:85], v[204:207], v[90:93]
	v_mfma_f32_16x16x32_bf16 v[90:93], v[146:149], v[208:211], v[86:89]
	v_mfma_f32_16x16x32_bf16 v[30:33], v[150:153], v[182:185], v[30:33]
	v_mfma_f32_16x16x32_bf16 v[30:33], v[154:157], v[192:195], v[30:33]
	v_mfma_f32_16x16x32_bf16 v[22:25], v[150:153], v[196:199], v[22:25]
	v_mfma_f32_16x16x32_bf16 v[22:25], v[154:157], v[200:203], v[22:25]
	v_mfma_f32_16x16x32_bf16 v[14:17], v[150:153], v[204:207], v[14:17]
	v_mfma_f32_16x16x32_bf16 v[14:17], v[154:157], v[208:211], v[14:17]
	v_mfma_f32_16x16x32_bf16 v[6:9], v[150:153], v[212:215], v[6:9]
	v_mfma_f32_16x16x32_bf16 v[6:9], v[154:157], v[224:227], v[6:9]
	v_mfma_f32_16x16x32_bf16 v[26:29], v[158:161], v[182:185], v[26:29]
	v_mfma_f32_16x16x32_bf16 v[26:29], v[178:181], v[192:195], v[26:29]
	v_mfma_f32_16x16x32_bf16 v[18:21], v[158:161], v[196:199], v[18:21]
	v_mfma_f32_16x16x32_bf16 v[18:21], v[178:181], v[200:203], v[18:21]
	v_mfma_f32_16x16x32_bf16 v[10:13], v[158:161], v[204:207], v[10:13]
	v_mfma_f32_16x16x32_bf16 v[10:13], v[178:181], v[208:211], v[10:13]
	v_mfma_f32_16x16x32_bf16 v[2:5], v[158:161], v[212:215], v[2:5]
	v_mfma_f32_16x16x32_bf16 v[2:5], v[178:181], v[224:227], v[2:5]
	v_mfma_f32_16x16x32_bf16 v[86:89], v[78:81], v[224:227], v[66:69]
	v_mfma_f32_16x16x32_bf16 v[66:69], v[82:85], v[212:215], v[70:73]
	v_mfma_f32_16x16x32_bf16 v[82:85], v[146:149], v[224:227], v[66:69]
	s_setprio 0
	s_barrier
	s_add_i32 s30, s30, 2
	s_add_u32 s28, s28, 0x100
	s_addc_u32 s29, s29, 0
	s_cmp_gt_u32 s30, 29
	s_mov_b64 s[0:1], s[2:3]
	s_cbranch_scc0 .LBB0_232
	s_and_b64 vcc, exec, s[44:45]
	s_cbranch_vccz .LBB0_235
	s_barrier

; #define PG8_STAGE(bufoff, gbase, voff) do { const char* gb_ = (const char*)(gbase); asm volatile("" : "+s"(gb_)); _Pragma("unroll") for (int _i = 0; _i < 2; ++_i) { unsigned vo_ = (voff)[_i]; asm volatile("" : "+v"(vo_));        \
;         __builtin_amdgcn_global_load_lds((const unsigned*)(gb_ + vo_), (PG8_LAS unsigned*)(lds + (bufoff) + ldsw + _i * 8192), 16, 0, 0); } } while (0)
; #define PG8_LDA(dst, b, h) do { _Pragma("unroll") for (int m = 0; m < 4; ++m) _Pragma("unroll") for (int k = 0; k < 2; ++k) dst[m][k] = *(const PG8_LAS bf16x8*)(lds + PG8_SA(b, h) + aoff + m * 2048 + k * 1024); } while (0)
; #define PG8_LDB(dst, b, h) do { _Pragma("unroll") for (int n = 0; n < 2; ++n) _Pragma("unroll") for (int k = 0; k < 2; ++k) dst[n][k] = *(const PG8_LAS bf16x8*)(lds + PG8_SB(b, h) + boff + n * 2048 + k * 1024); } while (0)
; #define PG8_MMA(ai, bj, At, Bt) do { __builtin_amdgcn_s_setprio(1); _Pragma("unroll") for (int m = 0; m < 4; ++m) _Pragma("unroll") for (int n = 0; n < 2; ++n) _Pragma("unroll") for (int k = 0; k < 2; ++k) \
;         acc[ai][bj][m][n] = __builtin_amdgcn_mfma_f32_16x16x32_bf16(Bt[n][k], At[m][k], acc[ai][bj][m][n], 0, 0, 0); __builtin_amdgcn_s_setprio(0); } while (0)
; #define PG8_WAIT_V(n) asm volatile("s_waitcnt vmcnt(" #n ")" ::: "memory")
; template <class Epi, class Sched, bool ALIGN_EPI = false, bool SP2 = false>
; __device__ __forceinline__ void gemm_phase(PG8_LAS unsigned char* lds, const Gemm g, const Sched& S, const Epi& E) {
;     ...
;             const bool last = (t == nt - 2);
;             const char* a1 = cA + (size_t)(t + 1) * kstep;
;             const char* a2 = last ? nA : cA + (size_t)(t + 2) * kstep; const char* b2 = last ? nB : cB + (size_t)(t + 2) * kstep;
;             const char* a3 = a2 + kstep; const char* b3 = b2 + kstep;
;             if (last && has_next) S.a_ready(nxt);
;             if constexpr (SP2) {
;             PG8_LDB(B0, 0, 0); PG8_LDB(B1, 0, 1); PG8_SCHED; PG8_LDA(At, 0, 0); PG8_STAGE(PG8_SA(1, 1), a1 + hstep, voffA);
;             PG8_WAIT_V(8); PG8_WAIT_L(0); PG8_BAR; PG8_MMA(0, 0, At, B0); PG8_MMA(0, 1, At, B1); PG8_BAR; PG8_SCHED;
;             PG8_LDA(At, 0, 1); PG8_STAGE(PG8_SB(0, 0), b2, voffB); PG8_STAGE(PG8_SB(0, 1), b2 + hstep, voffB); PG8_STAGE(PG8_SA(0, 0), a2, voffA);
;             PG8_WAIT_V(8); PG8_WAIT_L(0); PG8_BAR; PG8_MMA(1, 0, At, B0); PG8_MMA(1, 1, At, B1); PG8_BAR; PG8_SCHED;
.LBB0_555:
	s_add_u32 s6, s4, 0x100
	s_addc_u32 s7, s5, 0
	s_cmp_eq_u32 s51, 28
	s_cselect_b32 s12, s35, s6
	s_cselect_b32 s13, s34, s7
	s_cselect_b32 s10, s39, s40
	s_cselect_b32 s11, s38, s49
	s_add_u32 s8, s12, 0x80
	s_addc_u32 s9, s13, 0
	s_add_i32 s56, 0, 0x10000
	s_add_i32 s57, 0, 0x14000
	ds_read_b128 v[26:29], v244
	ds_read_b128 v[30:33], v244 offset:1024
	ds_read_b128 v[98:101], v244 offset:2048
	ds_read_b128 v[102:105], v244 offset:3072
	ds_read_b128 v[146:149], v244 offset:16384
	ds_read_b128 v[150:153], v244 offset:17408
	ds_read_b128 v[154:157], v244 offset:18432
	ds_read_b128 v[158:161], v244 offset:19456
	s_add_u32 s4, s4, 0x80080
	s_addc_u32 s5, s5, 0
	ds_read_b128 v[178:181], v210
	ds_read_b128 v[182:185], v210 offset:1024
	ds_read_b128 v[186:189], v210 offset:2048
	ds_read_b128 v[190:193], v210 offset:3072
	ds_read_b128 v[194:197], v210 offset:4096
	ds_read_b128 v[198:201], v210 offset:5120
	ds_read_b128 v[202:205], v210 offset:6144
	ds_read_b128 v[212:215], v210 offset:7168
	s_add_i32 m0, s18, 0xc000
	s_nop 0
	global_load_lds_dwordx4 v1, s[4:5]
	s_add_i32 m0, s18, 0xe000
	s_nop 0
	global_load_lds_dwordx4 v164, s[4:5]
	s_waitcnt vmcnt(8)
	s_waitcnt lgkmcnt(0)
	s_barrier
	s_setprio 1
	s_waitcnt lgkmcnt(0)
	v_mfma_f32_16x16x32_bf16 v[142:145], v[26:29], v[178:181], v[142:145]
	v_mfma_f32_16x16x32_bf16 v[142:145], v[30:33], v[182:185], v[142:145]
	v_mfma_f32_16x16x32_bf16 v[134:137], v[26:29], v[186:189], v[134:137]
	v_mfma_f32_16x16x32_bf16 v[134:137], v[30:33], v[190:193], v[134:137]
	v_mfma_f32_16x16x32_bf16 v[126:129], v[26:29], v[194:197], v[126:129]
	v_mfma_f32_16x16x32_bf16 v[126:129], v[30:33], v[198:201], v[126:129]
	v_mfma_f32_16x16x32_bf16 v[118:121], v[26:29], v[202:205], v[118:121]
	v_mfma_f32_16x16x32_bf16 v[118:121], v[30:33], v[212:215], v[118:121]
	v_mfma_f32_16x16x32_bf16 v[138:141], v[98:101], v[178:181], v[138:141]
	v_mfma_f32_16x16x32_bf16 v[138:141], v[102:105], v[182:185], v[138:141]
	v_mfma_f32_16x16x32_bf16 v[130:133], v[98:101], v[186:189], v[130:133]
	v_mfma_f32_16x16x32_bf16 v[130:133], v[102:105], v[190:193], v[130:133]
	v_mfma_f32_16x16x32_bf16 v[122:125], v[98:101], v[194:197], v[122:125]
	v_mfma_f32_16x16x32_bf16 v[122:125], v[102:105], v[198:201], v[122:125]
	v_mfma_f32_16x16x32_bf16 v[114:117], v[98:101], v[202:205], v[114:117]
	v_mfma_f32_16x16x32_bf16 v[114:117], v[102:105], v[212:215], v[114:117]
	v_mfma_f32_16x16x32_bf16 v[70:73], v[146:149], v[178:181], v[70:73]
	v_mfma_f32_16x16x32_bf16 v[70:73], v[150:153], v[182:185], v[70:73]
	v_mfma_f32_16x16x32_bf16 v[62:65], v[146:149], v[186:189], v[62:65]
	v_mfma_f32_16x16x32_bf16 v[62:65], v[150:153], v[190:193], v[62:65]
	v_mfma_f32_16x16x32_bf16 v[54:57], v[146:149], v[194:197], v[54:57]
	v_mfma_f32_16x16x32_bf16 v[54:57], v[150:153], v[198:201], v[54:57]
	v_mfma_f32_16x16x32_bf16 v[46:49], v[146:149], v[202:205], v[46:49]
	v_mfma_f32_16x16x32_bf16 v[46:49], v[150:153], v[212:215], v[46:49]
	v_mfma_f32_16x16x32_bf16 v[66:69], v[154:157], v[178:181], v[66:69]
	v_mfma_f32_16x16x32_bf16 v[66:69], v[158:161], v[182:185], v[66:69]
	v_mfma_f32_16x16x32_bf16 v[58:61], v[154:157], v[186:189], v[58:61]
	v_mfma_f32_16x16x32_bf16 v[58:61], v[158:161], v[190:193], v[58:61]
	v_mfma_f32_16x16x32_bf16 v[50:53], v[154:157], v[194:197], v[50:53]
	v_mfma_f32_16x16x32_bf16 v[50:53], v[158:161], v[198:201], v[50:53]
	v_mfma_f32_16x16x32_bf16 v[42:45], v[154:157], v[202:205], v[42:45]
	v_mfma_f32_16x16x32_bf16 v[42:45], v[158:161], v[212:215], v[42:45]
	s_setprio 0
	s_barrier
	s_mov_b64 s[4:5], s[10:11]
	s_add_i32 s56, s56, s17
	ds_read_b128 v[178:181], v210 offset:16384
	ds_read_b128 v[182:185], v210 offset:17408
	ds_read_b128 v[186:189], v210 offset:18432
	ds_read_b128 v[190:193], v210 offset:19456
	ds_read_b128 v[194:197], v210 offset:20480
	ds_read_b128 v[198:201], v210 offset:21504
	ds_read_b128 v[202:205], v210 offset:22528
	ds_read_b128 v[212:215], v210 offset:23552
	s_mov_b32 m0, s56
	s_nop 0
	global_load_lds_dwordx4 v162, s[4:5]
	s_add_i32 m0, s56, 0x2000
	s_nop 0
	global_load_lds_dwordx4 v206, s[4:5]
	s_add_u32 s4, s10, 0x80000
	s_addc_u32 s5, s11, 0
	s_add_i32 s56, s57, s17
	s_mov_b32 m0, s56
	s_nop 0
	global_load_lds_dwordx4 v162, s[4:5]
	s_add_i32 m0, s56, 0x2000
	s_nop 0
	global_load_lds_dwordx4 v206, s[4:5]
	s_mov_b64 s[4:5], s[12:13]
	s_mov_b32 m0, s18
	s_nop 0
	global_load_lds_dwordx4 v1, s[4:5]
	s_mov_b32 m0, s19
	s_nop 0
	global_load_lds_dwordx4 v164, s[4:5]
	s_waitcnt vmcnt(8)
	s_waitcnt lgkmcnt(0)
	s_barrier
	s_setprio 1
	s_waitcnt lgkmcnt(0)
	v_mfma_f32_16x16x32_bf16 v[110:113], v[26:29], v[178:181], v[110:113]
	v_mfma_f32_16x16x32_bf16 v[110:113], v[30:33], v[182:185], v[110:113]
	v_mfma_f32_16x16x32_bf16 v[94:97], v[26:29], v[186:189], v[94:97]
	v_mfma_f32_16x16x32_bf16 v[94:97], v[30:33], v[190:193], v[94:97]
	v_mfma_f32_16x16x32_bf16 v[86:89], v[26:29], v[194:197], v[86:89]
	v_mfma_f32_16x16x32_bf16 v[86:89], v[30:33], v[198:201], v[86:89]
	v_mfma_f32_16x16x32_bf16 v[26:29], v[26:29], v[202:205], v[78:81]
	v_mfma_f32_16x16x32_bf16 v[26:29], v[30:33], v[212:215], v[26:29]
	v_mfma_f32_16x16x32_bf16 v[106:109], v[98:101], v[178:181], v[106:109]
	v_mfma_f32_16x16x32_bf16 v[106:109], v[102:105], v[182:185], v[106:109]
	v_mfma_f32_16x16x32_bf16 v[90:93], v[98:101], v[186:189], v[90:93]
	v_mfma_f32_16x16x32_bf16 v[90:93], v[102:105], v[190:193], v[90:93]
	v_mfma_f32_16x16x32_bf16 v[82:85], v[98:101], v[194:197], v[82:85]
	v_mfma_f32_16x16x32_bf16 v[82:85], v[102:105], v[198:201], v[82:85]
	v_mfma_f32_16x16x32_bf16 v[30:33], v[98:101], v[202:205], v[74:77]
	v_mfma_f32_16x16x32_bf16 v[30:33], v[102:105], v[212:215], v[30:33]
	v_mfma_f32_16x16x32_bf16 v[38:41], v[146:149], v[178:181], v[38:41]
	v_mfma_f32_16x16x32_bf16 v[38:41], v[150:153], v[182:185], v[38:41]
	v_mfma_f32_16x16x32_bf16 v[22:25], v[146:149], v[186:189], v[22:25]
	v_mfma_f32_16x16x32_bf16 v[22:25], v[150:153], v[190:193], v[22:25]
	v_mfma_f32_16x16x32_bf16 v[14:17], v[146:149], v[194:197], v[14:17]
	v_mfma_f32_16x16x32_bf16 v[14:17], v[150:153], v[198:201], v[14:17]
	v_mfma_f32_16x16x32_bf16 v[6:9], v[146:149], v[202:205], v[6:9]
	v_mfma_f32_16x16x32_bf16 v[6:9], v[150:153], v[212:215], v[6:9]
	v_mfma_f32_16x16x32_bf16 v[34:37], v[154:157], v[178:181], v[34:37]
	v_mfma_f32_16x16x32_bf16 v[34:37], v[158:161], v[182:185], v[34:37]
	v_mfma_f32_16x16x32_bf16 v[18:21], v[154:157], v[186:189], v[18:21]
	v_mfma_f32_16x16x32_bf16 v[18:21], v[158:161], v[190:193], v[18:21]
	v_mfma_f32_16x16x32_bf16 v[10:13], v[154:157], v[194:197], v[10:13]
	v_mfma_f32_16x16x32_bf16 v[10:13], v[158:161], v[198:201], v[10:13]
	v_mfma_f32_16x16x32_bf16 v[2:5], v[154:157], v[202:205], v[2:5]
	v_mfma_f32_16x16x32_bf16 v[2:5], v[158:161], v[212:215], v[2:5]
	s_setprio 0
	s_barrier
; #define PG8_STAGE(bufoff, gbase, voff) do { const char* gb_ = (const char*)(gbase); asm volatile("" : "+s"(gb_)); _Pragma("unroll") for (int _i = 0; _i < 2; ++_i) { unsigned vo_ = (voff)[_i]; asm volatile("" : "+v"(vo_));        \
;         __builtin_amdgcn_global_load_lds((const unsigned*)(gb_ + vo_), (PG8_LAS unsigned*)(lds + (bufoff) + ldsw + _i * 8192), 16, 0, 0); } } while (0)
; #define PG8_LDA(dst, b, h) do { _Pragma("unroll") for (int m = 0; m < 4; ++m) _Pragma("unroll") for (int k = 0; k < 2; ++k) dst[m][k] = *(const PG8_LAS bf16x8*)(lds + PG8_SA(b, h) + aoff + m * 2048 + k * 1024); } while (0)
; #define PG8_LDB(dst, b, h) do { _Pragma("unroll") for (int n = 0; n < 2; ++n) _Pragma("unroll") for (int k = 0; k < 2; ++k) dst[n][k] = *(const PG8_LAS bf16x8*)(lds + PG8_SB(b, h) + boff + n * 2048 + k * 1024); } while (0)
; #define PG8_MMA(ai, bj, At, Bt) do { __builtin_amdgcn_s_setprio(1); _Pragma("unroll") for (int m = 0; m < 4; ++m) _Pragma("unroll") for (int n = 0; n < 2; ++n) _Pragma("unroll") for (int k = 0; k < 2; ++k) \
;         acc[ai][bj][m][n] = __builtin_amdgcn_mfma_f32_16x16x32_bf16(Bt[n][k], At[m][k], acc[ai][bj][m][n], 0, 0, 0); __builtin_amdgcn_s_setprio(0); } while (0)
; #define PG8_WAIT_V(n) asm volatile("s_waitcnt vmcnt(" #n ")" ::: "memory")
; #define PG8_WAIT_L(n) asm volatile("s_waitcnt lgkmcnt(" #n ")" ::: "memory")
; #define PG8_BAR __builtin_amdgcn_s_barrier()
; #define PG8_SCHED __builtin_amdgcn_sched_barrier(0)
; template <class Epi, class Sched, bool ALIGN_EPI = false, bool SP2 = false>
; __device__ __forceinline__ void gemm_phase(PG8_LAS unsigned char* lds, const Gemm g, const Sched& S, const Epi& E) {
;     ...
;             PG8_LDB(B0, 1, 0); PG8_LDB(B1, 1, 1); PG8_SCHED; PG8_LDA(At, 1, 0); PG8_STAGE(PG8_SA(0, 1), a2 + hstep, voffA);
;             PG8_WAIT_V(8); PG8_WAIT_L(0); PG8_BAR; PG8_MMA(0, 0, At, B0); PG8_MMA(0, 1, At, B1); PG8_BAR; PG8_SCHED;
;             PG8_LDA(At, 1, 1); PG8_STAGE(PG8_SB(1, 0), b3, voffB); PG8_STAGE(PG8_SB(1, 1), b3 + hstep, voffB); PG8_STAGE(PG8_SA(1, 0), a3, voffA);
;             PG8_WAIT_V(8); PG8_WAIT_L(0); PG8_BAR; PG8_MMA(1, 0, At, B0); PG8_MMA(1, 1, At, B1); PG8_BAR; PG8_SCHED;
	s_add_i32 s56, 0, 0x18000
	s_add_i32 s57, 0, 0x1c000
	ds_read_b128 v[74:77], v244 offset:32768
	ds_read_b128 v[78:81], v244 offset:33792
	ds_read_b128 v[98:101], v244 offset:34816
	ds_read_b128 v[102:105], v244 offset:35840
	ds_read_b128 v[146:149], v244 offset:49152
	ds_read_b128 v[150:153], v244 offset:50176
	ds_read_b128 v[154:157], v244 offset:51200
	ds_read_b128 v[158:161], v244 offset:52224
	s_add_u32 s4, s12, 0x80000
	s_addc_u32 s5, s13, 0
	s_mov_b32 m0, s20
	ds_read_b128 v[178:181], v210 offset:32768
	ds_read_b128 v[182:185], v210 offset:33792
	ds_read_b128 v[186:189], v210 offset:34816
	ds_read_b128 v[190:193], v210 offset:35840
	ds_read_b128 v[194:197], v210 offset:36864
	ds_read_b128 v[198:201], v210 offset:37888
	ds_read_b128 v[202:205], v210 offset:38912
	ds_read_b128 v[212:215], v210 offset:39936
	s_nop 0
	global_load_lds_dwordx4 v1, s[4:5]
	s_mov_b32 m0, s21
	s_nop 0
	global_load_lds_dwordx4 v164, s[4:5]
	s_waitcnt vmcnt(8)
	s_waitcnt lgkmcnt(0)
	s_barrier
	s_setprio 1
	s_waitcnt lgkmcnt(0)
	v_mfma_f32_16x16x32_bf16 v[142:145], v[74:77], v[178:181], v[142:145]
	v_mfma_f32_16x16x32_bf16 v[142:145], v[78:81], v[182:185], v[142:145]
	v_mfma_f32_16x16x32_bf16 v[134:137], v[74:77], v[186:189], v[134:137]
	v_mfma_f32_16x16x32_bf16 v[134:137], v[78:81], v[190:193], v[134:137]
	v_mfma_f32_16x16x32_bf16 v[126:129], v[74:77], v[194:197], v[126:129]
	v_mfma_f32_16x16x32_bf16 v[126:129], v[78:81], v[198:201], v[126:129]
	v_mfma_f32_16x16x32_bf16 v[118:121], v[74:77], v[202:205], v[118:121]
	v_mfma_f32_16x16x32_bf16 v[118:121], v[78:81], v[212:215], v[118:121]
	v_mfma_f32_16x16x32_bf16 v[138:141], v[98:101], v[178:181], v[138:141]
	v_mfma_f32_16x16x32_bf16 v[138:141], v[102:105], v[182:185], v[138:141]
	v_mfma_f32_16x16x32_bf16 v[130:133], v[98:101], v[186:189], v[130:133]
	v_mfma_f32_16x16x32_bf16 v[130:133], v[102:105], v[190:193], v[130:133]
	v_mfma_f32_16x16x32_bf16 v[122:125], v[98:101], v[194:197], v[122:125]
	v_mfma_f32_16x16x32_bf16 v[122:125], v[102:105], v[198:201], v[122:125]
	v_mfma_f32_16x16x32_bf16 v[114:117], v[98:101], v[202:205], v[114:117]
	v_mfma_f32_16x16x32_bf16 v[114:117], v[102:105], v[212:215], v[114:117]
	v_mfma_f32_16x16x32_bf16 v[70:73], v[146:149], v[178:181], v[70:73]
	v_mfma_f32_16x16x32_bf16 v[70:73], v[150:153], v[182:185], v[70:73]
	v_mfma_f32_16x16x32_bf16 v[62:65], v[146:149], v[186:189], v[62:65]
	v_mfma_f32_16x16x32_bf16 v[62:65], v[150:153], v[190:193], v[62:65]
	v_mfma_f32_16x16x32_bf16 v[54:57], v[146:149], v[194:197], v[54:57]
	v_mfma_f32_16x16x32_bf16 v[54:57], v[150:153], v[198:201], v[54:57]
	v_mfma_f32_16x16x32_bf16 v[46:49], v[146:149], v[202:205], v[46:49]
	v_mfma_f32_16x16x32_bf16 v[46:49], v[150:153], v[212:215], v[46:49]
	v_mfma_f32_16x16x32_bf16 v[66:69], v[154:157], v[178:181], v[66:69]
	v_mfma_f32_16x16x32_bf16 v[66:69], v[158:161], v[182:185], v[66:69]
	v_mfma_f32_16x16x32_bf16 v[58:61], v[154:157], v[186:189], v[58:61]
	v_mfma_f32_16x16x32_bf16 v[58:61], v[158:161], v[190:193], v[58:61]
	v_mfma_f32_16x16x32_bf16 v[50:53], v[154:157], v[194:197], v[50:53]
	v_mfma_f32_16x16x32_bf16 v[50:53], v[158:161], v[198:201], v[50:53]
	v_mfma_f32_16x16x32_bf16 v[42:45], v[154:157], v[202:205], v[42:45]
	v_mfma_f32_16x16x32_bf16 v[42:45], v[158:161], v[212:215], v[42:45]
	s_setprio 0
	s_barrier
	s_add_u32 s4, s10, 0x80
	s_addc_u32 s5, s11, 0
	s_add_i32 s12, s56, s17
	ds_read_b128 v[178:181], v210 offset:49152
	ds_read_b128 v[182:185], v210 offset:50176
	ds_read_b128 v[186:189], v210 offset:51200
	ds_read_b128 v[190:193], v210 offset:52224
	ds_read_b128 v[194:197], v210 offset:53248
	ds_read_b128 v[198:201], v210 offset:54272
	ds_read_b128 v[202:205], v210 offset:55296
	ds_read_b128 v[212:215], v210 offset:56320
	s_mov_b32 m0, s12
	s_nop 0
	global_load_lds_dwordx4 v162, s[4:5]
	s_add_i32 m0, s12, 0x2000
	s_nop 0
	global_load_lds_dwordx4 v206, s[4:5]
	s_add_u32 s4, s10, 0x80080
	s_addc_u32 s5, s11, 0
	s_add_i32 s10, s57, s17
	s_mov_b32 m0, s10
	s_nop 0
	global_load_lds_dwordx4 v162, s[4:5]
	s_add_i32 m0, s10, 0x2000
	s_nop 0
	global_load_lds_dwordx4 v206, s[4:5]
	s_mov_b32 m0, s26
	s_nop 0
	global_load_lds_dwordx4 v1, s[8:9]
	s_mov_b32 m0, s27
	s_nop 0
	global_load_lds_dwordx4 v164, s[8:9]
	s_waitcnt vmcnt(8)
	s_waitcnt lgkmcnt(0)
	s_barrier
	s_setprio 1
	s_waitcnt lgkmcnt(0)
	v_mfma_f32_16x16x32_bf16 v[110:113], v[74:77], v[178:181], v[110:113]
	v_mfma_f32_16x16x32_bf16 v[110:113], v[78:81], v[182:185], v[110:113]
	v_mfma_f32_16x16x32_bf16 v[94:97], v[74:77], v[186:189], v[94:97]
	v_mfma_f32_16x16x32_bf16 v[94:97], v[78:81], v[190:193], v[94:97]
	v_mfma_f32_16x16x32_bf16 v[86:89], v[74:77], v[194:197], v[86:89]
	v_mfma_f32_16x16x32_bf16 v[86:89], v[78:81], v[198:201], v[86:89]
	v_mfma_f32_16x16x32_bf16 v[26:29], v[74:77], v[202:205], v[26:29]
	v_mfma_f32_16x16x32_bf16 v[78:81], v[78:81], v[212:215], v[26:29]
	v_mfma_f32_16x16x32_bf16 v[106:109], v[98:101], v[178:181], v[106:109]
	v_mfma_f32_16x16x32_bf16 v[106:109], v[102:105], v[182:185], v[106:109]
	v_mfma_f32_16x16x32_bf16 v[90:93], v[98:101], v[186:189], v[90:93]
	v_mfma_f32_16x16x32_bf16 v[90:93], v[102:105], v[190:193], v[90:93]
	v_mfma_f32_16x16x32_bf16 v[82:85], v[98:101], v[194:197], v[82:85]
	v_mfma_f32_16x16x32_bf16 v[82:85], v[102:105], v[198:201], v[82:85]
	v_mfma_f32_16x16x32_bf16 v[26:29], v[98:101], v[202:205], v[30:33]
	v_mfma_f32_16x16x32_bf16 v[74:77], v[102:105], v[212:215], v[26:29]
	v_mfma_f32_16x16x32_bf16 v[26:29], v[146:149], v[178:181], v[38:41]
	v_mfma_f32_16x16x32_bf16 v[38:41], v[150:153], v[182:185], v[26:29]
	v_mfma_f32_16x16x32_bf16 v[22:25], v[146:149], v[186:189], v[22:25]
	v_mfma_f32_16x16x32_bf16 v[22:25], v[150:153], v[190:193], v[22:25]
	v_mfma_f32_16x16x32_bf16 v[14:17], v[146:149], v[194:197], v[14:17]
	v_mfma_f32_16x16x32_bf16 v[14:17], v[150:153], v[198:201], v[14:17]
	v_mfma_f32_16x16x32_bf16 v[6:9], v[146:149], v[202:205], v[6:9]
	v_mfma_f32_16x16x32_bf16 v[6:9], v[150:153], v[212:215], v[6:9]
	v_mfma_f32_16x16x32_bf16 v[26:29], v[154:157], v[178:181], v[34:37]
	v_mfma_f32_16x16x32_bf16 v[34:37], v[158:161], v[182:185], v[26:29]
	v_mfma_f32_16x16x32_bf16 v[18:21], v[154:157], v[186:189], v[18:21]
	v_mfma_f32_16x16x32_bf16 v[18:21], v[158:161], v[190:193], v[18:21]
	v_mfma_f32_16x16x32_bf16 v[10:13], v[154:157], v[194:197], v[10:13]
	v_mfma_f32_16x16x32_bf16 v[10:13], v[158:161], v[198:201], v[10:13]
	v_mfma_f32_16x16x32_bf16 v[2:5], v[154:157], v[202:205], v[2:5]
	v_mfma_f32_16x16x32_bf16 v[2:5], v[158:161], v[212:215], v[2:5]
	s_setprio 0
	s_barrier
;     __device__ __forceinline__ void operator()(const f32x4 (&acc)[2][2][4][2], const Unit& u, int wr, int wc, int fr, int fq) const {
;         const int row0 = u.pm * BM + wr * 64 + fr, col0 = u.pn * BM + wc * 32 + 8 * fq, b = (u.pm * BM) / rows_per_batch;
;         const float* g = gate + (size_t)b * gate_bstride + col0;
;         float ssq[2][4];
; #pragma unroll
;         for (int ai = 0; ai < 2; ++ai)
; #pragma unroll
;             for (int m = 0; m < 4; ++m) ssq[ai][m] = 0.f;
;         f32x4 gv[2][2], Gv[2][2];
; #pragma unroll
;         for (int bj = 0; bj < 2; ++bj) { gv[bj][0] = *(const f32x4*)(g + bj * HALF); gv[bj][1] = *(const f32x4*)(g + bj * HALF + 4); Gv[bj][0] = (f32x4){0.f, 0.f, 0.f, 0.f}; Gv[bj][1] = (f32x4){0.f, 0.f, 0.f, 0.f};
;             if (Hn) { const float* sc = scnext + (size_t)b * gate_bstride + col0 + bj * HALF;
;                 Gv[bj][0] = *(const f32x4*)(gnext + col0 + bj * HALF) * (1.0f + *(const f32x4*)(sc)); Gv[bj][1] = *(const f32x4*)(gnext + col0 + bj * HALF + 4) * (1.0f + *(const f32x4*)(sc + 4)); } }
; #pragma unroll
;         for (int bj = 0; bj < 2; ++bj) {
;             const f32x4 g0 = gv[bj][0], g1 = gv[bj][1], G0 = Gv[bj][0], G1 = Gv[bj][1];
; #pragma unroll
;             for (int ai = 0; ai < 2; ++ai)
; #pragma unroll
;                 for (int m = 0; m < 4; ++m) { const size_t off = (size_t)(row0 + ai * HALF + m * 16) * 2048 + col0 + bj * HALF;
;                     f32x4 x0 = __builtin_nontemporal_load((const f32x4*)(base + off)), x1 = __builtin_nontemporal_load((const f32x4*)(base + off + 4));
;                     if constexpr (HAS_DIN) { const u32x4 dw = __builtin_nontemporal_load((const u32x4*)(dbuf + off));
;                         x0 += (f32x4){__builtin_bit_cast(float, dw.x << 16), __builtin_bit_cast(float, dw.x & 0xffff0000u), __builtin_bit_cast(float, dw.y << 16), __builtin_bit_cast(float, dw.y & 0xffff0000u)};
;                         x1 += (f32x4){__builtin_bit_cast(float, dw.z << 16), __builtin_bit_cast(float, dw.z & 0xffff0000u), __builtin_bit_cast(float, dw.w << 16), __builtin_bit_cast(float, dw.w & 0xffff0000u)}; }
;                     f32x4 o0, o1;
;                     if constexpr (OUT_DELTA) { const f32x4 d0 = g0 * acc[ai][bj][m][0], d1 = g1 * acc[ai][bj][m][1];
	s_add_i32 s51, s51, 2
	s_add_u32 s40, s40, 0x100
	s_addc_u32 s49, s49, 0
	s_cmp_gt_u32 s51, 29
	s_mov_b64 s[4:5], s[6:7]
	s_cbranch_scc0 .LBB0_555
	s_ashr_i32 s4, s29, 31
	s_lshr_b32 s4, s4, 27
	s_add_i32 s4, s29, s4
	s_ashr_i32 s4, s4, 5
	v_lshl_or_b32 v148, s33, 8, v209
	s_mul_i32 s7, s4, 0xc000
	v_ashrrev_i32_e32 v149, 31, v148
	s_mul_hi_i32 s6, s4, 0xc000
	s_add_u32 s4, s22, s7
	s_addc_u32 s5, s23, s6
	v_lshlrev_b64 v[26:27], 2, v[148:149]
	v_lshl_add_u64 v[146:147], s[4:5], 0, v[26:27]
	s_add_u32 s4, s24, s7
	s_addc_u32 s5, s25, s6
	v_lshl_add_u64 v[160:161], s[4:5], 0, v[26:27]
	v_lshl_add_u64 v[178:179], s[46:47], 0, v[26:27]
	global_load_dwordx4 v[98:101], v[146:147], off offset:16
	global_load_dwordx4 v[102:105], v[146:147], off
	global_load_dwordx4 v[26:29], v[178:179], off offset:16
	global_load_dwordx4 v[30:33], v[178:179], off
	global_load_dwordx4 v[150:153], v[160:161], off offset:16
	global_load_dwordx4 v[154:157], v[160:161], off
	s_mov_b64 s[4:5], 0x40000
	s_waitcnt vmcnt(0)
	v_pk_mul_f32 v[188:189], v[140:141], v[100:101]
	v_pk_mul_f32 v[142:143], v[142:143], v[102:103]
	v_pk_mul_f32 v[144:145], v[144:145], v[104:105]
	v_pk_mul_f32 v[140:141], v[138:139], v[98:99]
	v_pk_mul_f32 v[136:137], v[136:137], v[104:105]
	v_pk_add_f32 v[156:157], v[156:157], 1.0 op_sel_hi:[1,0]
	v_pk_add_f32 v[154:155], v[154:155], 1.0 op_sel_hi:[1,0]
	v_pk_mul_f32 v[198:199], v[32:33], v[156:157]
	v_pk_mul_f32 v[200:201], v[30:31], v[154:155]
	v_pk_add_f32 v[30:31], v[152:153], 1.0 op_sel_hi:[1,0]
	v_pk_add_f32 v[32:33], v[150:151], 1.0 op_sel_hi:[1,0]
	v_pk_mul_f32 v[202:203], v[28:29], v[30:31]
	v_pk_mul_f32 v[204:205], v[26:27], v[32:33]
	global_load_dwordx4 v[26:29], v[146:147], off offset:528
	global_load_dwordx4 v[30:33], v[146:147], off offset:512
	global_load_dwordx4 v[156:159], v[178:179], off offset:528
	global_load_dwordx4 v[152:155], v[178:179], off offset:512
	s_nop 0
	global_load_dwordx4 v[178:181], v[160:161], off offset:528
	global_load_dwordx4 v[182:185], v[160:161], off offset:512
	v_pk_mul_f32 v[134:135], v[134:135], v[102:103]
	v_pk_mul_f32 v[130:131], v[130:131], v[98:99]
	v_pk_mul_f32 v[132:133], v[132:133], v[100:101]
	v_pk_mul_f32 v[128:129], v[128:129], v[104:105]
	v_pk_mul_f32 v[126:127], v[126:127], v[102:103]
	v_pk_mul_f32 v[122:123], v[122:123], v[98:99]
	v_pk_mul_f32 v[124:125], v[124:125], v[100:101]
	v_pk_mul_f32 v[120:121], v[120:121], v[104:105]
	v_pk_mul_f32 v[118:119], v[118:119], v[102:103]
	v_pk_mul_f32 v[114:115], v[114:115], v[98:99]
	v_pk_mul_f32 v[116:117], v[116:117], v[100:101]
	v_pk_mul_f32 v[112:113], v[112:113], v[104:105]
	v_pk_mul_f32 v[110:111], v[110:111], v[102:103]
	v_pk_mul_f32 v[106:107], v[106:107], v[98:99]
	v_pk_mul_f32 v[108:109], v[108:109], v[100:101]
	v_pk_mul_f32 v[96:97], v[96:97], v[104:105]
	v_pk_mul_f32 v[94:95], v[94:95], v[102:103]
	v_pk_mul_f32 v[90:91], v[90:91], v[98:99]
	v_pk_mul_f32 v[92:93], v[92:93], v[100:101]
	v_pk_mul_f32 v[88:89], v[88:89], v[104:105]
	v_pk_mul_f32 v[86:87], v[86:87], v[102:103]
	v_pk_mul_f32 v[82:83], v[82:83], v[98:99]
	v_pk_mul_f32 v[84:85], v[84:85], v[100:101]
	v_pk_mul_f32 v[80:81], v[80:81], v[104:105]
	v_pk_mul_f32 v[78:79], v[78:79], v[102:103]
	v_pk_mul_f32 v[74:75], v[74:75], v[98:99]
	v_pk_mul_f32 v[76:77], v[76:77], v[100:101]
	s_waitcnt vmcnt(5)
	v_pk_mul_f32 v[58:59], v[58:59], v[26:27]
	s_waitcnt vmcnt(4)
	v_pk_mul_f32 v[72:73], v[72:73], v[32:33]
	v_pk_mul_f32 v[70:71], v[70:71], v[30:31]
	v_pk_mul_f32 v[64:65], v[64:65], v[32:33]
	v_pk_mul_f32 v[62:63], v[62:63], v[30:31]
	s_waitcnt vmcnt(0)
	v_pk_add_f32 v[146:147], v[184:185], 1.0 op_sel_hi:[1,0]
	v_pk_add_f32 v[160:161], v[182:183], 1.0 op_sel_hi:[1,0]
	v_pk_mul_f32 v[150:151], v[154:155], v[146:147]
	v_pk_add_f32 v[146:147], v[180:181], 1.0 op_sel_hi:[1,0]
	v_pk_mul_f32 v[152:153], v[152:153], v[160:161]
	v_pk_mul_f32 v[154:155], v[158:159], v[146:147]
	v_lshl_add_u32 v146, s29, 8, v207
	v_ashrrev_i32_e32 v147, 31, v146
	v_lshlrev_b64 v[184:185], 11, v[146:147]
	v_lshl_add_u64 v[186:187], v[184:185], 0, v[148:149]
	v_pk_add_f32 v[160:161], v[178:179], 1.0 op_sel_hi:[1,0]
	v_lshl_add_u64 v[178:179], v[186:187], 2, s[44:45]
	v_pk_mul_f32 v[156:157], v[156:157], v[160:161]
	global_load_dwordx4 v[158:161], v[178:179], off nt
	global_load_dwordx4 v[180:183], v[178:179], off offset:16 nt
	v_cvt_pk_bf16_f32 v138, v142, v143
	v_lshlrev_b64 v[142:143], 1, v[186:187]
	v_cvt_pk_bf16_f32 v139, v144, v145
	v_cvt_pk_bf16_f32 v140, v140, v141
	v_cvt_pk_bf16_f32 v141, v188, v189
	v_lshl_add_u64 v[144:145], s[90:91], 0, v[142:143]
	global_store_dwordx4 v[144:145], v[138:141], off
	v_lshlrev_b32_e32 v144, 16, v140
	v_and_b32_e32 v145, 0xffff0000, v140
	v_lshlrev_b32_e32 v140, 16, v141
	v_and_b32_e32 v141, 0xffff0000, v141
	v_lshl_add_u64 v[142:143], s[96:97], 0, v[142:143]
	v_pk_mul_f32 v[60:61], v[60:61], v[28:29]
	v_pk_mul_f32 v[56:57], v[56:57], v[32:33]
	v_pk_mul_f32 v[54:55], v[54:55], v[30:31]
	v_pk_mul_f32 v[50:51], v[50:51], v[26:27]
	v_pk_mul_f32 v[52:53], v[52:53], v[28:29]
	v_pk_mul_f32 v[48:49], v[48:49], v[32:33]
	v_pk_mul_f32 v[46:47], v[46:47], v[30:31]
	v_pk_mul_f32 v[42:43], v[42:43], v[26:27]
	v_pk_mul_f32 v[44:45], v[44:45], v[28:29]
	v_pk_mul_f32 v[40:41], v[40:41], v[32:33]
	v_pk_mul_f32 v[38:39], v[38:39], v[30:31]
	v_pk_mul_f32 v[34:35], v[34:35], v[26:27]
	v_pk_mul_f32 v[36:37], v[36:37], v[28:29]
	v_pk_mul_f32 v[24:25], v[24:25], v[32:33]
	v_pk_mul_f32 v[22:23], v[22:23], v[30:31]
	v_pk_mul_f32 v[18:19], v[18:19], v[26:27]
	v_pk_mul_f32 v[20:21], v[20:21], v[28:29]
	v_pk_mul_f32 v[16:17], v[16:17], v[32:33]
	v_pk_mul_f32 v[14:15], v[14:15], v[30:31]
	v_pk_mul_f32 v[10:11], v[10:11], v[26:27]
	v_pk_mul_f32 v[12:13], v[12:13], v[28:29]
	v_pk_mul_f32 v[8:9], v[8:9], v[32:33]
	v_pk_mul_f32 v[6:7], v[6:7], v[30:31]
	v_pk_mul_f32 v[2:3], v[2:3], v[26:27]
	v_pk_mul_f32 v[4:5], v[4:5], v[28:29]
	s_waitcnt vmcnt(1)
; __device__ __forceinline__ unsigned cvt_pk_bf16(float lo, float hi) { unsigned r; asm volatile("v_cvt_pk_bf16_f32 %0, %1, %2" : "=v"(r) : "v"(lo), "v"(hi)); return r; }
;     __device__ __forceinline__ void operator()(const f32x4 (&acc)[2][2][4][2], const Unit& u, int wr, int wc, int fr, int fq) const {
;     ...
;                 for (int m = 0; m < 4; ++m) { const size_t off = (size_t)(row0 + ai * HALF + m * 16) * 2048 + col0 + bj * HALF;
;                     f32x4 x0 = __builtin_nontemporal_load((const f32x4*)(base + off)), x1 = __builtin_nontemporal_load((const f32x4*)(base + off + 4));
;                     if constexpr (HAS_DIN) { const u32x4 dw = __builtin_nontemporal_load((const u32x4*)(dbuf + off));
;                         x0 += (f32x4){__builtin_bit_cast(float, dw.x << 16), __builtin_bit_cast(float, dw.x & 0xffff0000u), __builtin_bit_cast(float, dw.y << 16), __builtin_bit_cast(float, dw.y & 0xffff0000u)};
;                         x1 += (f32x4){__builtin_bit_cast(float, dw.z << 16), __builtin_bit_cast(float, dw.z & 0xffff0000u), __builtin_bit_cast(float, dw.w << 16), __builtin_bit_cast(float, dw.w & 0xffff0000u)}; }
;                     f32x4 o0, o1;
;                     if constexpr (OUT_DELTA) { const f32x4 d0 = g0 * acc[ai][bj][m][0], d1 = g1 * acc[ai][bj][m][1];
;                         u32x4 w; w.x = cvt_pk_bf16(d0[0], d0[1]); w.y = cvt_pk_bf16(d0[2], d0[3]); w.z = cvt_pk_bf16(d1[0], d1[1]); w.w = cvt_pk_bf16(d1[2], d1[3]);
;                         *(u32x4*)(dbuf + off) = w;
;                         o0 = x0 + (f32x4){__builtin_bit_cast(float, w.x << 16), __builtin_bit_cast(float, w.x & 0xffff0000u), __builtin_bit_cast(float, w.y << 16), __builtin_bit_cast(float, w.y & 0xffff0000u)};
;                         o1 = x1 + (f32x4){__builtin_bit_cast(float, w.z << 16), __builtin_bit_cast(float, w.z & 0xffff0000u), __builtin_bit_cast(float, w.w << 16), __builtin_bit_cast(float, w.w & 0xffff0000u)}; }
;                     else { o0 = x0 + g0 * acc[ai][bj][m][0]; o1 = x1 + g1 * acc[ai][bj][m][1]; *(f32x4*)(out + off) = o0; *(f32x4*)(out + off + 4) = o1; }
;                     if (Hn) { const f32x4 h0 = o0 * G0, h1 = o1 * G1;
;                         u32x4 w; w.x = cvt_pk_bf16(h0[0], h0[1]); w.y = cvt_pk_bf16(h0[2], h0[3]); w.z = cvt_pk_bf16(h1[0], h1[1]); w.w = cvt_pk_bf16(h1[2], h1[3]);
;                         *(u32x4*)(Hn + off) = w;
	v_pk_add_f32 v[182:183], v[182:183], v[140:141]
	v_lshlrev_b32_e32 v140, 16, v138
	v_and_b32_e32 v141, 0xffff0000, v138
	v_lshlrev_b32_e32 v138, 16, v139
	v_and_b32_e32 v139, 0xffff0000, v139
	v_pk_add_f32 v[158:159], v[158:159], v[140:141]
	v_pk_add_f32 v[160:161], v[160:161], v[138:139]
	v_pk_mul_f32 v[138:139], v[200:201], v[158:159]
	v_pk_add_f32 v[144:145], v[180:181], v[144:145]
	v_pk_mul_f32 v[140:141], v[198:199], v[160:161]
	v_cvt_pk_bf16_f32 v138, v138, v139
	v_pk_mul_f32 v[180:181], v[202:203], v[182:183]
	v_cvt_pk_bf16_f32 v139, v140, v141
	v_pk_mul_f32 v[186:187], v[204:205], v[144:145]
	s_nop 0
	v_cvt_pk_bf16_f32 v140, v186, v187
	v_cvt_pk_bf16_f32 v141, v180, v181
	global_store_dwordx4 v[142:143], v[138:141], off
	s_nop 1
	v_mul_f32_e32 v138, v159, v159
	v_mul_f32_e32 v139, v161, v161
	v_fmac_f32_e32 v138, v158, v158
	v_fmac_f32_e32 v139, v160, v160
	v_add_f32_e32 v138, v138, v139
	v_mul_f32_e32 v139, v145, v145
	v_mul_f32_e32 v140, v183, v183
	v_fmac_f32_e32 v139, v144, v144
	v_fmac_f32_e32 v140, v182, v182
	v_add_f32_e32 v139, v139, v140
	v_add_f32_e32 v211, v138, v139
	v_or_b32_e32 v138, 16, v146
	v_ashrrev_i32_e32 v139, 31, v138
	v_lshlrev_b64 v[140:141], 11, v[138:139]
	v_lshl_add_u64 v[180:181], v[140:141], 0, v[148:149]
	v_lshl_add_u64 v[138:139], v[180:181], 2, s[44:45]
	global_load_dwordx4 v[142:145], v[138:139], off nt
	global_load_dwordx4 v[158:161], v[138:139], off offset:16 nt
	v_lshlrev_b64 v[180:181], 1, v[180:181]
	v_cvt_pk_bf16_f32 v134, v134, v135
	v_cvt_pk_bf16_f32 v135, v136, v137
	v_cvt_pk_bf16_f32 v136, v130, v131
	v_cvt_pk_bf16_f32 v137, v132, v133
	v_lshl_add_u64 v[130:131], s[90:91], 0, v[180:181]
	global_store_dwordx4 v[130:131], v[134:137], off
	v_lshlrev_b32_e32 v132, 16, v136
	v_and_b32_e32 v133, 0xffff0000, v136
	v_lshlrev_b32_e32 v130, 16, v137
	v_and_b32_e32 v131, 0xffff0000, v137
	v_lshlrev_b32_e32 v136, 16, v134
	v_and_b32_e32 v137, 0xffff0000, v134
	v_lshlrev_b32_e32 v134, 16, v135
	v_and_b32_e32 v135, 0xffff0000, v135
	s_waitcnt vmcnt(2)
	v_pk_add_f32 v[134:135], v[144:145], v[134:135]
	s_waitcnt vmcnt(1)
	v_pk_add_f32 v[130:131], v[160:161], v[130:131]
	v_pk_add_f32 v[136:137], v[142:143], v[136:137]
	v_pk_add_f32 v[132:133], v[158:159], v[132:133]
	v_pk_mul_f32 v[144:145], v[198:199], v[134:135]
	v_pk_mul_f32 v[142:143], v[200:201], v[136:137]
	v_pk_mul_f32 v[158:159], v[202:203], v[130:131]
	v_pk_mul_f32 v[160:161], v[204:205], v[132:133]
	v_cvt_pk_bf16_f32 v142, v142, v143
	v_cvt_pk_bf16_f32 v143, v144, v145
	s_nop 0
	v_cvt_pk_bf16_f32 v144, v160, v161
	v_cvt_pk_bf16_f32 v145, v158, v159
	v_lshl_add_u64 v[158:159], s[96:97], 0, v[180:181]
	global_store_dwordx4 v[158:159], v[142:145], off
	s_nop 1
	v_or_b32_e32 v142, 32, v146
	v_ashrrev_i32_e32 v143, 31, v142
	v_lshlrev_b64 v[144:145], 11, v[142:143]
	v_lshl_add_u64 v[186:187], v[144:145], 0, v[148:149]
	v_lshl_add_u64 v[142:143], v[186:187], 2, s[44:45]
	global_load_dwordx4 v[158:161], v[142:143], off nt
	global_load_dwordx4 v[180:183], v[142:143], off offset:16 nt
	v_lshlrev_b64 v[186:187], 1, v[186:187]
	v_cvt_pk_bf16_f32 v126, v126, v127
	v_cvt_pk_bf16_f32 v127, v128, v129
	v_cvt_pk_bf16_f32 v128, v122, v123
	v_cvt_pk_bf16_f32 v129, v124, v125
	v_lshl_add_u64 v[122:123], s[90:91], 0, v[186:187]
	global_store_dwordx4 v[122:123], v[126:129], off
	v_lshlrev_b32_e32 v124, 16, v128
	v_and_b32_e32 v125, 0xffff0000, v128
	v_lshlrev_b32_e32 v122, 16, v129
	v_and_b32_e32 v123, 0xffff0000, v129
	v_lshlrev_b32_e32 v128, 16, v126
	v_and_b32_e32 v129, 0xffff0000, v126
	v_lshlrev_b32_e32 v126, 16, v127
	v_and_b32_e32 v127, 0xffff0000, v127
	s_waitcnt vmcnt(2)
	v_pk_add_f32 v[126:127], v[160:161], v[126:127]
	s_waitcnt vmcnt(1)
	v_pk_add_f32 v[122:123], v[182:183], v[122:123]
	v_pk_add_f32 v[128:129], v[158:159], v[128:129]
	v_pk_add_f32 v[124:125], v[180:181], v[124:125]
	v_pk_mul_f32 v[160:161], v[198:199], v[126:127]
	v_pk_mul_f32 v[158:159], v[200:201], v[128:129]
	v_pk_mul_f32 v[180:181], v[202:203], v[122:123]
	v_pk_mul_f32 v[182:183], v[204:205], v[124:125]
	v_cvt_pk_bf16_f32 v158, v158, v159
	v_cvt_pk_bf16_f32 v159, v160, v161
	s_nop 0
	v_cvt_pk_bf16_f32 v160, v182, v183
	v_cvt_pk_bf16_f32 v161, v180, v181
	v_lshl_add_u64 v[180:181], s[96:97], 0, v[186:187]
	global_store_dwordx4 v[180:181], v[158:161], off
	s_nop 1
	v_or_b32_e32 v158, 48, v146
	v_ashrrev_i32_e32 v159, 31, v158
	v_lshlrev_b64 v[160:161], 11, v[158:159]
	v_lshl_add_u64 v[190:191], v[160:161], 0, v[148:149]
	v_lshl_add_u64 v[158:159], v[190:191], 2, s[44:45]
	global_load_dwordx4 v[180:183], v[158:159], off nt
	global_load_dwordx4 v[186:189], v[158:159], off offset:16 nt
	v_lshlrev_b64 v[190:191], 1, v[190:191]
	v_cvt_pk_bf16_f32 v118, v118, v119
	v_cvt_pk_bf16_f32 v119, v120, v121
	v_cvt_pk_bf16_f32 v120, v114, v115
	v_cvt_pk_bf16_f32 v121, v116, v117
	v_lshl_add_u64 v[114:115], s[90:91], 0, v[190:191]
	global_store_dwordx4 v[114:115], v[118:121], off
	v_lshlrev_b32_e32 v116, 16, v120
	v_and_b32_e32 v117, 0xffff0000, v120
	v_lshlrev_b32_e32 v114, 16, v121
	v_and_b32_e32 v115, 0xffff0000, v121
	v_lshlrev_b32_e32 v120, 16, v118
	v_and_b32_e32 v121, 0xffff0000, v118
	v_lshlrev_b32_e32 v118, 16, v119
	v_and_b32_e32 v119, 0xffff0000, v119
	s_waitcnt vmcnt(2)
	v_pk_add_f32 v[118:119], v[182:183], v[118:119]
	s_waitcnt vmcnt(1)
; __device__ __forceinline__ unsigned cvt_pk_bf16(float lo, float hi) { unsigned r; asm volatile("v_cvt_pk_bf16_f32 %0, %1, %2" : "=v"(r) : "v"(lo), "v"(hi)); return r; }
;     __device__ __forceinline__ void operator()(const f32x4 (&acc)[2][2][4][2], const Unit& u, int wr, int wc, int fr, int fq) const {
;     ...
;                 for (int m = 0; m < 4; ++m) { const size_t off = (size_t)(row0 + ai * HALF + m * 16) * 2048 + col0 + bj * HALF;
;                     f32x4 x0 = __builtin_nontemporal_load((const f32x4*)(base + off)), x1 = __builtin_nontemporal_load((const f32x4*)(base + off + 4));
;                     if constexpr (HAS_DIN) { const u32x4 dw = __builtin_nontemporal_load((const u32x4*)(dbuf + off));
;                         x0 += (f32x4){__builtin_bit_cast(float, dw.x << 16), __builtin_bit_cast(float, dw.x & 0xffff0000u), __builtin_bit_cast(float, dw.y << 16), __builtin_bit_cast(float, dw.y & 0xffff0000u)};
;                         x1 += (f32x4){__builtin_bit_cast(float, dw.z << 16), __builtin_bit_cast(float, dw.z & 0xffff0000u), __builtin_bit_cast(float, dw.w << 16), __builtin_bit_cast(float, dw.w & 0xffff0000u)}; }
;                     f32x4 o0, o1;
;                     if constexpr (OUT_DELTA) { const f32x4 d0 = g0 * acc[ai][bj][m][0], d1 = g1 * acc[ai][bj][m][1];
;                         u32x4 w; w.x = cvt_pk_bf16(d0[0], d0[1]); w.y = cvt_pk_bf16(d0[2], d0[3]); w.z = cvt_pk_bf16(d1[0], d1[1]); w.w = cvt_pk_bf16(d1[2], d1[3]);
;                         *(u32x4*)(dbuf + off) = w;
;                         o0 = x0 + (f32x4){__builtin_bit_cast(float, w.x << 16), __builtin_bit_cast(float, w.x & 0xffff0000u), __builtin_bit_cast(float, w.y << 16), __builtin_bit_cast(float, w.y & 0xffff0000u)};
;                         o1 = x1 + (f32x4){__builtin_bit_cast(float, w.z << 16), __builtin_bit_cast(float, w.z & 0xffff0000u), __builtin_bit_cast(float, w.w << 16), __builtin_bit_cast(float, w.w & 0xffff0000u)}; }
;                     else { o0 = x0 + g0 * acc[ai][bj][m][0]; o1 = x1 + g1 * acc[ai][bj][m][1]; *(f32x4*)(out + off) = o0; *(f32x4*)(out + off + 4) = o1; }
;                     if (Hn) { const f32x4 h0 = o0 * G0, h1 = o1 * G1;
;                         u32x4 w; w.x = cvt_pk_bf16(h0[0], h0[1]); w.y = cvt_pk_bf16(h0[2], h0[3]); w.z = cvt_pk_bf16(h1[0], h1[1]); w.w = cvt_pk_bf16(h1[2], h1[3]);
;                         *(u32x4*)(Hn + off) = w;
	v_pk_add_f32 v[114:115], v[188:189], v[114:115]
	v_pk_add_f32 v[120:121], v[180:181], v[120:121]
	v_pk_add_f32 v[116:117], v[186:187], v[116:117]
	v_pk_mul_f32 v[182:183], v[198:199], v[118:119]
	v_pk_mul_f32 v[180:181], v[200:201], v[120:121]
	v_pk_mul_f32 v[186:187], v[202:203], v[114:115]
	v_pk_mul_f32 v[188:189], v[204:205], v[116:117]
	v_cvt_pk_bf16_f32 v180, v180, v181
	v_cvt_pk_bf16_f32 v181, v182, v183
	s_nop 0
	v_cvt_pk_bf16_f32 v182, v188, v189
	v_cvt_pk_bf16_f32 v183, v186, v187
	v_lshl_add_u64 v[186:187], s[96:97], 0, v[190:191]
	global_store_dwordx4 v[186:187], v[180:183], off
	s_nop 1
	v_lshl_add_u64 v[182:183], v[184:185], 0, s[4:5]
	v_lshl_add_u64 v[194:195], v[182:183], 0, v[148:149]
	v_lshl_add_u64 v[180:181], v[194:195], 2, s[44:45]
	global_load_dwordx4 v[186:189], v[180:181], off nt
	global_load_dwordx4 v[190:193], v[180:181], off offset:16 nt
	v_lshlrev_b64 v[194:195], 1, v[194:195]
	v_cvt_pk_bf16_f32 v110, v110, v111
	v_cvt_pk_bf16_f32 v111, v112, v113
	v_cvt_pk_bf16_f32 v112, v106, v107
	v_cvt_pk_bf16_f32 v113, v108, v109
	v_lshl_add_u64 v[106:107], s[90:91], 0, v[194:195]
	global_store_dwordx4 v[106:107], v[110:113], off
	v_lshlrev_b32_e32 v108, 16, v112
	v_and_b32_e32 v109, 0xffff0000, v112
	v_lshlrev_b32_e32 v106, 16, v113
	v_and_b32_e32 v107, 0xffff0000, v113
	v_lshlrev_b32_e32 v112, 16, v110
	v_and_b32_e32 v113, 0xffff0000, v110
	v_lshlrev_b32_e32 v110, 16, v111
	v_and_b32_e32 v111, 0xffff0000, v111
	s_mov_b64 s[4:5], 0x48000
	s_waitcnt vmcnt(2)
	v_pk_add_f32 v[110:111], v[188:189], v[110:111]
	s_waitcnt vmcnt(1)
	v_pk_add_f32 v[106:107], v[192:193], v[106:107]
	v_pk_add_f32 v[112:113], v[186:187], v[112:113]
	v_pk_add_f32 v[108:109], v[190:191], v[108:109]
	v_pk_mul_f32 v[188:189], v[198:199], v[110:111]
	v_pk_mul_f32 v[186:187], v[200:201], v[112:113]
	v_pk_mul_f32 v[190:191], v[202:203], v[106:107]
	v_pk_mul_f32 v[192:193], v[204:205], v[108:109]
	v_cvt_pk_bf16_f32 v186, v186, v187
	v_cvt_pk_bf16_f32 v187, v188, v189
	s_nop 0
	v_cvt_pk_bf16_f32 v188, v192, v193
	v_cvt_pk_bf16_f32 v189, v190, v191
	v_lshl_add_u64 v[190:191], s[96:97], 0, v[194:195]
	global_store_dwordx4 v[190:191], v[186:189], off
	s_nop 1
	v_lshl_add_u64 v[188:189], v[184:185], 0, s[4:5]
	v_lshl_add_u64 v[212:213], v[188:189], 0, v[148:149]
	v_lshl_add_u64 v[186:187], v[212:213], 2, s[44:45]
	global_load_dwordx4 v[190:193], v[186:187], off nt
	global_load_dwordx4 v[194:197], v[186:187], off offset:16 nt
	v_lshlrev_b64 v[212:213], 1, v[212:213]
	v_cvt_pk_bf16_f32 v94, v94, v95
	v_cvt_pk_bf16_f32 v95, v96, v97
	v_cvt_pk_bf16_f32 v96, v90, v91
	v_cvt_pk_bf16_f32 v97, v92, v93
	v_lshl_add_u64 v[90:91], s[90:91], 0, v[212:213]
	global_store_dwordx4 v[90:91], v[94:97], off
	v_lshlrev_b32_e32 v92, 16, v96
	v_and_b32_e32 v93, 0xffff0000, v96
	v_lshlrev_b32_e32 v90, 16, v97
	v_and_b32_e32 v91, 0xffff0000, v97
	v_lshlrev_b32_e32 v96, 16, v94
	v_and_b32_e32 v97, 0xffff0000, v94
	v_lshlrev_b32_e32 v94, 16, v95
	v_and_b32_e32 v95, 0xffff0000, v95
	s_mov_b64 s[4:5], 0x50000
	s_waitcnt vmcnt(2)
	v_pk_add_f32 v[94:95], v[192:193], v[94:95]
	s_waitcnt vmcnt(1)
	v_pk_add_f32 v[90:91], v[196:197], v[90:91]
	v_pk_add_f32 v[96:97], v[190:191], v[96:97]
	v_pk_add_f32 v[92:93], v[194:195], v[92:93]
	v_pk_mul_f32 v[192:193], v[198:199], v[94:95]
	v_pk_mul_f32 v[190:191], v[200:201], v[96:97]
	v_pk_mul_f32 v[194:195], v[202:203], v[90:91]
	v_pk_mul_f32 v[196:197], v[204:205], v[92:93]
	v_cvt_pk_bf16_f32 v190, v190, v191
	v_cvt_pk_bf16_f32 v191, v192, v193
	s_nop 0
	v_cvt_pk_bf16_f32 v192, v196, v197
	v_cvt_pk_bf16_f32 v193, v194, v195
	v_lshl_add_u64 v[194:195], s[96:97], 0, v[212:213]
	global_store_dwordx4 v[194:195], v[190:193], off
	s_nop 1
	v_lshl_add_u64 v[192:193], v[184:185], 0, s[4:5]
	v_lshl_add_u64 v[220:221], v[192:193], 0, v[148:149]
	v_lshl_add_u64 v[190:191], v[220:221], 2, s[44:45]
	global_load_dwordx4 v[194:197], v[190:191], off nt
	global_load_dwordx4 v[212:215], v[190:191], off offset:16 nt
	v_lshlrev_b64 v[220:221], 1, v[220:221]
	v_cvt_pk_bf16_f32 v86, v86, v87
	v_cvt_pk_bf16_f32 v87, v88, v89
	v_cvt_pk_bf16_f32 v88, v82, v83
	v_cvt_pk_bf16_f32 v89, v84, v85
	v_lshl_add_u64 v[82:83], s[90:91], 0, v[220:221]
	global_store_dwordx4 v[82:83], v[86:89], off
	v_lshlrev_b32_e32 v84, 16, v88
	v_and_b32_e32 v85, 0xffff0000, v88
	v_lshlrev_b32_e32 v82, 16, v89
	v_and_b32_e32 v83, 0xffff0000, v89
	v_lshlrev_b32_e32 v88, 16, v86
	v_and_b32_e32 v89, 0xffff0000, v86
	v_lshlrev_b32_e32 v86, 16, v87
	v_and_b32_e32 v87, 0xffff0000, v87
	s_mov_b64 s[4:5], 0x58000
	s_waitcnt vmcnt(2)
	v_pk_add_f32 v[86:87], v[196:197], v[86:87]
	s_waitcnt vmcnt(1)
	v_pk_add_f32 v[82:83], v[214:215], v[82:83]
	v_pk_add_f32 v[88:89], v[194:195], v[88:89]
	v_pk_add_f32 v[84:85], v[212:213], v[84:85]
	v_pk_mul_f32 v[196:197], v[198:199], v[86:87]
	v_pk_mul_f32 v[194:195], v[200:201], v[88:89]
	v_pk_mul_f32 v[212:213], v[202:203], v[82:83]
	v_pk_mul_f32 v[214:215], v[204:205], v[84:85]
	v_cvt_pk_bf16_f32 v194, v194, v195
	v_cvt_pk_bf16_f32 v195, v196, v197
	s_nop 0
	v_cvt_pk_bf16_f32 v196, v214, v215
	v_cvt_pk_bf16_f32 v197, v212, v213
	v_lshl_add_u64 v[212:213], s[96:97], 0, v[220:221]
	global_store_dwordx4 v[212:213], v[194:197], off
	s_nop 1
	v_lshl_add_u64 v[196:197], v[184:185], 0, s[4:5]
	v_lshl_add_u64 v[224:225], v[196:197], 0, v[148:149]
	v_lshl_add_u64 v[194:195], v[224:225], 2, s[44:45]
	global_load_dwordx4 v[212:215], v[194:195], off nt
	global_load_dwordx4 v[220:223], v[194:195], off offset:16 nt
	v_lshlrev_b64 v[102:103], 1, v[224:225]
	v_cvt_pk_bf16_f32 v78, v78, v79
	v_cvt_pk_bf16_f32 v79, v80, v81
	v_cvt_pk_bf16_f32 v80, v74, v75
	v_cvt_pk_bf16_f32 v81, v76, v77
	v_lshl_add_u64 v[74:75], s[90:91], 0, v[102:103]
	global_store_dwordx4 v[74:75], v[78:81], off
	v_lshlrev_b32_e32 v76, 16, v80
	v_and_b32_e32 v77, 0xffff0000, v80
	v_lshlrev_b32_e32 v74, 16, v81
	v_and_b32_e32 v75, 0xffff0000, v81
	v_lshlrev_b32_e32 v80, 16, v78
	v_and_b32_e32 v81, 0xffff0000, v78
	v_lshlrev_b32_e32 v78, 16, v79
	v_and_b32_e32 v79, 0xffff0000, v79
	v_lshl_add_u64 v[102:103], s[96:97], 0, v[102:103]
	v_or_b32_e32 v148, 0x80, v148
	s_waitcnt vmcnt(2)
; __device__ __forceinline__ unsigned cvt_pk_bf16(float lo, float hi) { unsigned r; asm volatile("v_cvt_pk_bf16_f32 %0, %1, %2" : "=v"(r) : "v"(lo), "v"(hi)); return r; }
;     __device__ __forceinline__ void operator()(const f32x4 (&acc)[2][2][4][2], const Unit& u, int wr, int wc, int fr, int fq) const {
;     ...
;                 for (int m = 0; m < 4; ++m) { const size_t off = (size_t)(row0 + ai * HALF + m * 16) * 2048 + col0 + bj * HALF;
;                     f32x4 x0 = __builtin_nontemporal_load((const f32x4*)(base + off)), x1 = __builtin_nontemporal_load((const f32x4*)(base + off + 4));
;                     if constexpr (HAS_DIN) { const u32x4 dw = __builtin_nontemporal_load((const u32x4*)(dbuf + off));
;                         x0 += (f32x4){__builtin_bit_cast(float, dw.x << 16), __builtin_bit_cast(float, dw.x & 0xffff0000u), __builtin_bit_cast(float, dw.y << 16), __builtin_bit_cast(float, dw.y & 0xffff0000u)};
;                         x1 += (f32x4){__builtin_bit_cast(float, dw.z << 16), __builtin_bit_cast(float, dw.z & 0xffff0000u), __builtin_bit_cast(float, dw.w << 16), __builtin_bit_cast(float, dw.w & 0xffff0000u)}; }
;                     f32x4 o0, o1;
;                     if constexpr (OUT_DELTA) { const f32x4 d0 = g0 * acc[ai][bj][m][0], d1 = g1 * acc[ai][bj][m][1];
;                         u32x4 w; w.x = cvt_pk_bf16(d0[0], d0[1]); w.y = cvt_pk_bf16(d0[2], d0[3]); w.z = cvt_pk_bf16(d1[0], d1[1]); w.w = cvt_pk_bf16(d1[2], d1[3]);
;                         *(u32x4*)(dbuf + off) = w;
;                         o0 = x0 + (f32x4){__builtin_bit_cast(float, w.x << 16), __builtin_bit_cast(float, w.x & 0xffff0000u), __builtin_bit_cast(float, w.y << 16), __builtin_bit_cast(float, w.y & 0xffff0000u)};
;                         o1 = x1 + (f32x4){__builtin_bit_cast(float, w.z << 16), __builtin_bit_cast(float, w.z & 0xffff0000u), __builtin_bit_cast(float, w.w << 16), __builtin_bit_cast(float, w.w & 0xffff0000u)}; }
;                     else { o0 = x0 + g0 * acc[ai][bj][m][0]; o1 = x1 + g1 * acc[ai][bj][m][1]; *(f32x4*)(out + off) = o0; *(f32x4*)(out + off + 4) = o1; }
;                     if (Hn) { const f32x4 h0 = o0 * G0, h1 = o1 * G1;
;                         u32x4 w; w.x = cvt_pk_bf16(h0[0], h0[1]); w.y = cvt_pk_bf16(h0[2], h0[3]); w.z = cvt_pk_bf16(h1[0], h1[1]); w.w = cvt_pk_bf16(h1[2], h1[3]);
;                         *(u32x4*)(Hn + off) = w;
	v_pk_add_f32 v[78:79], v[214:215], v[78:79]
	v_pk_add_f32 v[80:81], v[212:213], v[80:81]
	s_waitcnt vmcnt(1)
	v_pk_add_f32 v[74:75], v[222:223], v[74:75]
	v_pk_add_f32 v[76:77], v[220:221], v[76:77]
	v_pk_mul_f32 v[100:101], v[198:199], v[78:79]
	v_pk_mul_f32 v[98:99], v[200:201], v[80:81]
	v_pk_mul_f32 v[104:105], v[202:203], v[74:75]
	v_pk_mul_f32 v[198:199], v[204:205], v[76:77]
	v_cvt_pk_bf16_f32 v98, v98, v99
	v_cvt_pk_bf16_f32 v99, v100, v101
	s_nop 0
	v_cvt_pk_bf16_f32 v100, v198, v199
	v_cvt_pk_bf16_f32 v101, v104, v105
	global_store_dwordx4 v[102:103], v[98:101], off
	global_load_dwordx4 v[100:103], v[178:179], off offset:512 nt
	global_load_dwordx4 v[198:201], v[178:179], off offset:528 nt
	v_lshl_add_u64 v[98:99], v[184:185], 0, v[148:149]
	v_pk_mul_f32 v[104:105], v[68:69], v[28:29]
	v_pk_mul_f32 v[68:69], v[66:67], v[26:27]
	v_cvt_pk_bf16_f32 v66, v70, v71
	v_cvt_pk_bf16_f32 v67, v72, v73
	s_nop 0
	v_cvt_pk_bf16_f32 v68, v68, v69
	v_cvt_pk_bf16_f32 v69, v104, v105
	v_lshlrev_b64 v[104:105], 1, v[98:99]
	v_lshl_add_u64 v[70:71], s[90:91], 0, v[104:105]
	global_store_dwordx4 v[70:71], v[66:69], off
	v_lshlrev_b32_e32 v72, 16, v68
	v_and_b32_e32 v73, 0xffff0000, v68
	v_lshlrev_b32_e32 v68, 16, v69
	v_and_b32_e32 v69, 0xffff0000, v69
	s_waitcnt vmcnt(1)
	v_pk_add_f32 v[70:71], v[200:201], v[68:69]
	v_lshlrev_b32_e32 v68, 16, v66
	v_and_b32_e32 v69, 0xffff0000, v66
	v_lshlrev_b32_e32 v66, 16, v67
	v_and_b32_e32 v67, 0xffff0000, v67
	v_pk_add_f32 v[98:99], v[102:103], v[66:67]
	v_pk_add_f32 v[100:101], v[100:101], v[68:69]
	v_pk_add_f32 v[72:73], v[198:199], v[72:73]
	v_pk_mul_f32 v[68:69], v[150:151], v[98:99]
	v_pk_mul_f32 v[66:67], v[152:153], v[100:101]
	v_pk_mul_f32 v[102:103], v[154:155], v[70:71]
	v_pk_mul_f32 v[178:179], v[156:157], v[72:73]
	v_cvt_pk_bf16_f32 v66, v66, v67
	v_cvt_pk_bf16_f32 v67, v68, v69
	s_nop 0
	v_cvt_pk_bf16_f32 v68, v178, v179
	v_cvt_pk_bf16_f32 v69, v102, v103
	v_lshl_add_u64 v[102:103], s[96:97], 0, v[104:105]
	global_store_dwordx4 v[102:103], v[66:69], off
	s_nop 1
	v_mul_f32_e32 v66, v101, v101
	v_mul_f32_e32 v67, v99, v99
	v_fmac_f32_e32 v66, v100, v100
	v_fmac_f32_e32 v67, v98, v98
	v_add_f32_e32 v66, v66, v67
	v_mul_f32_e32 v67, v73, v73
	v_mul_f32_e32 v68, v71, v71
	v_fmac_f32_e32 v67, v72, v72
	v_fmac_f32_e32 v68, v70, v70
	v_add_f32_e32 v67, v67, v68
	global_load_dwordx4 v[68:71], v[138:139], off offset:512 nt
	global_load_dwordx4 v[98:101], v[138:139], off offset:528 nt
	v_lshl_add_u64 v[72:73], v[140:141], 0, v[148:149]
	v_lshlrev_b64 v[72:73], 1, v[72:73]
	v_cvt_pk_bf16_f32 v62, v62, v63
	v_cvt_pk_bf16_f32 v63, v64, v65
	v_cvt_pk_bf16_f32 v64, v58, v59
	v_cvt_pk_bf16_f32 v65, v60, v61
	v_lshl_add_u64 v[58:59], s[90:91], 0, v[72:73]
	global_store_dwordx4 v[58:59], v[62:65], off
	v_lshlrev_b32_e32 v60, 16, v64
	v_and_b32_e32 v61, 0xffff0000, v64
	v_lshlrev_b32_e32 v58, 16, v65
	v_and_b32_e32 v59, 0xffff0000, v65
	v_lshlrev_b32_e32 v64, 16, v62
	v_and_b32_e32 v65, 0xffff0000, v62
	v_lshlrev_b32_e32 v62, 16, v63
	v_and_b32_e32 v63, 0xffff0000, v63
	v_lshl_add_u64 v[72:73], s[96:97], 0, v[72:73]
	v_add_f32_e32 v66, v66, v67
	v_add_f32_e32 v66, v211, v66
	s_waitcnt vmcnt(2)
	v_pk_add_f32 v[62:63], v[70:71], v[62:63]
	v_pk_add_f32 v[64:65], v[68:69], v[64:65]
	s_waitcnt vmcnt(1)
	v_pk_add_f32 v[58:59], v[100:101], v[58:59]
	v_pk_add_f32 v[60:61], v[98:99], v[60:61]
	v_pk_mul_f32 v[70:71], v[150:151], v[62:63]
	v_pk_mul_f32 v[68:69], v[152:153], v[64:65]
	v_pk_mul_f32 v[98:99], v[154:155], v[58:59]
	v_pk_mul_f32 v[100:101], v[156:157], v[60:61]
	v_cvt_pk_bf16_f32 v68, v68, v69
	v_cvt_pk_bf16_f32 v69, v70, v71
	s_nop 0
	v_cvt_pk_bf16_f32 v70, v100, v101
	v_cvt_pk_bf16_f32 v71, v98, v99
	global_store_dwordx4 v[72:73], v[68:71], off
	global_load_dwordx4 v[68:71], v[142:143], off offset:512 nt
	s_nop 0
	global_load_dwordx4 v[98:101], v[142:143], off offset:528 nt
	v_lshl_add_u64 v[72:73], v[144:145], 0, v[148:149]
	v_lshlrev_b64 v[72:73], 1, v[72:73]
	v_cvt_pk_bf16_f32 v54, v54, v55
	v_cvt_pk_bf16_f32 v55, v56, v57
	v_cvt_pk_bf16_f32 v56, v50, v51
	v_cvt_pk_bf16_f32 v57, v52, v53
	v_lshl_add_u64 v[50:51], s[90:91], 0, v[72:73]
	global_store_dwordx4 v[50:51], v[54:57], off
	v_lshlrev_b32_e32 v52, 16, v56
	v_and_b32_e32 v53, 0xffff0000, v56
	v_lshlrev_b32_e32 v50, 16, v57
	v_and_b32_e32 v51, 0xffff0000, v57
	v_lshlrev_b32_e32 v56, 16, v54
	v_and_b32_e32 v57, 0xffff0000, v54
	v_lshlrev_b32_e32 v54, 16, v55
	v_and_b32_e32 v55, 0xffff0000, v55
	v_lshl_add_u64 v[72:73], s[96:97], 0, v[72:73]
	s_waitcnt vmcnt(2)
	v_pk_add_f32 v[54:55], v[70:71], v[54:55]
	v_pk_add_f32 v[56:57], v[68:69], v[56:57]
	s_waitcnt vmcnt(1)
	v_pk_add_f32 v[50:51], v[100:101], v[50:51]
	v_pk_add_f32 v[52:53], v[98:99], v[52:53]
	v_pk_mul_f32 v[70:71], v[150:151], v[54:55]
	v_pk_mul_f32 v[68:69], v[152:153], v[56:57]
	v_pk_mul_f32 v[98:99], v[154:155], v[50:51]
	v_pk_mul_f32 v[100:101], v[156:157], v[52:53]
	v_cvt_pk_bf16_f32 v68, v68, v69
	v_cvt_pk_bf16_f32 v69, v70, v71
	s_nop 0
	v_cvt_pk_bf16_f32 v70, v100, v101
	v_cvt_pk_bf16_f32 v71, v98, v99
	global_store_dwordx4 v[72:73], v[68:71], off
	global_load_dwordx4 v[68:71], v[158:159], off offset:512 nt
	s_nop 0
	global_load_dwordx4 v[98:101], v[158:159], off offset:528 nt
	v_lshl_add_u64 v[72:73], v[160:161], 0, v[148:149]
	v_lshlrev_b64 v[72:73], 1, v[72:73]
	v_cvt_pk_bf16_f32 v46, v46, v47
	v_cvt_pk_bf16_f32 v47, v48, v49
	v_cvt_pk_bf16_f32 v48, v42, v43
	v_cvt_pk_bf16_f32 v49, v44, v45
	v_lshl_add_u64 v[42:43], s[90:91], 0, v[72:73]
	global_store_dwordx4 v[42:43], v[46:49], off
	v_lshlrev_b32_e32 v44, 16, v48
	v_and_b32_e32 v45, 0xffff0000, v48
	v_lshlrev_b32_e32 v42, 16, v49
	v_and_b32_e32 v43, 0xffff0000, v49
	v_lshlrev_b32_e32 v48, 16, v46
	v_and_b32_e32 v49, 0xffff0000, v46
	v_lshlrev_b32_e32 v46, 16, v47
	v_and_b32_e32 v47, 0xffff0000, v47
	v_lshl_add_u64 v[72:73], s[96:97], 0, v[72:73]
	s_waitcnt vmcnt(2)
; __device__ __forceinline__ unsigned cvt_pk_bf16(float lo, float hi) { unsigned r; asm volatile("v_cvt_pk_bf16_f32 %0, %1, %2" : "=v"(r) : "v"(lo), "v"(hi)); return r; }
;     __device__ __forceinline__ void operator()(const f32x4 (&acc)[2][2][4][2], const Unit& u, int wr, int wc, int fr, int fq) const {
;     ...
;                 for (int m = 0; m < 4; ++m) { const size_t off = (size_t)(row0 + ai * HALF + m * 16) * 2048 + col0 + bj * HALF;
;                     f32x4 x0 = __builtin_nontemporal_load((const f32x4*)(base + off)), x1 = __builtin_nontemporal_load((const f32x4*)(base + off + 4));
;                     if constexpr (HAS_DIN) { const u32x4 dw = __builtin_nontemporal_load((const u32x4*)(dbuf + off));
;                         x0 += (f32x4){__builtin_bit_cast(float, dw.x << 16), __builtin_bit_cast(float, dw.x & 0xffff0000u), __builtin_bit_cast(float, dw.y << 16), __builtin_bit_cast(float, dw.y & 0xffff0000u)};
;                         x1 += (f32x4){__builtin_bit_cast(float, dw.z << 16), __builtin_bit_cast(float, dw.z & 0xffff0000u), __builtin_bit_cast(float, dw.w << 16), __builtin_bit_cast(float, dw.w & 0xffff0000u)}; }
;                     f32x4 o0, o1;
;                     if constexpr (OUT_DELTA) { const f32x4 d0 = g0 * acc[ai][bj][m][0], d1 = g1 * acc[ai][bj][m][1];
;                         u32x4 w; w.x = cvt_pk_bf16(d0[0], d0[1]); w.y = cvt_pk_bf16(d0[2], d0[3]); w.z = cvt_pk_bf16(d1[0], d1[1]); w.w = cvt_pk_bf16(d1[2], d1[3]);
;                         *(u32x4*)(dbuf + off) = w;
;                         o0 = x0 + (f32x4){__builtin_bit_cast(float, w.x << 16), __builtin_bit_cast(float, w.x & 0xffff0000u), __builtin_bit_cast(float, w.y << 16), __builtin_bit_cast(float, w.y & 0xffff0000u)};
;                         o1 = x1 + (f32x4){__builtin_bit_cast(float, w.z << 16), __builtin_bit_cast(float, w.z & 0xffff0000u), __builtin_bit_cast(float, w.w << 16), __builtin_bit_cast(float, w.w & 0xffff0000u)}; }
;                     else { o0 = x0 + g0 * acc[ai][bj][m][0]; o1 = x1 + g1 * acc[ai][bj][m][1]; *(f32x4*)(out + off) = o0; *(f32x4*)(out + off + 4) = o1; }
;                     if (Hn) { const f32x4 h0 = o0 * G0, h1 = o1 * G1;
;                         u32x4 w; w.x = cvt_pk_bf16(h0[0], h0[1]); w.y = cvt_pk_bf16(h0[2], h0[3]); w.z = cvt_pk_bf16(h1[0], h1[1]); w.w = cvt_pk_bf16(h1[2], h1[3]);
;                         *(u32x4*)(Hn + off) = w;
	v_pk_add_f32 v[46:47], v[70:71], v[46:47]
	v_pk_add_f32 v[48:49], v[68:69], v[48:49]
	s_waitcnt vmcnt(1)
	v_pk_add_f32 v[42:43], v[100:101], v[42:43]
	v_pk_add_f32 v[44:45], v[98:99], v[44:45]
	v_pk_mul_f32 v[70:71], v[150:151], v[46:47]
	v_pk_mul_f32 v[68:69], v[152:153], v[48:49]
	v_pk_mul_f32 v[98:99], v[154:155], v[42:43]
	v_pk_mul_f32 v[100:101], v[156:157], v[44:45]
	v_cvt_pk_bf16_f32 v68, v68, v69
	v_cvt_pk_bf16_f32 v69, v70, v71
	s_nop 0
	v_cvt_pk_bf16_f32 v70, v100, v101
	v_cvt_pk_bf16_f32 v71, v98, v99
	global_store_dwordx4 v[72:73], v[68:71], off
	global_load_dwordx4 v[68:71], v[180:181], off offset:512 nt
	s_nop 0
	global_load_dwordx4 v[98:101], v[180:181], off offset:528 nt
	v_lshl_add_u64 v[72:73], v[182:183], 0, v[148:149]
	v_lshlrev_b64 v[72:73], 1, v[72:73]
	v_cvt_pk_bf16_f32 v38, v38, v39
	v_cvt_pk_bf16_f32 v39, v40, v41
	v_cvt_pk_bf16_f32 v40, v34, v35
	v_cvt_pk_bf16_f32 v41, v36, v37
	v_lshl_add_u64 v[34:35], s[90:91], 0, v[72:73]
	global_store_dwordx4 v[34:35], v[38:41], off
	v_lshlrev_b32_e32 v36, 16, v40
	v_and_b32_e32 v37, 0xffff0000, v40
	v_lshlrev_b32_e32 v34, 16, v41
	v_and_b32_e32 v35, 0xffff0000, v41
	v_lshlrev_b32_e32 v40, 16, v38
	v_and_b32_e32 v41, 0xffff0000, v38
	v_lshlrev_b32_e32 v38, 16, v39
	v_and_b32_e32 v39, 0xffff0000, v39
	v_lshl_add_u64 v[72:73], s[96:97], 0, v[72:73]
	s_waitcnt vmcnt(2)
	v_pk_add_f32 v[38:39], v[70:71], v[38:39]
	v_pk_add_f32 v[40:41], v[68:69], v[40:41]
	s_waitcnt vmcnt(1)
	v_pk_add_f32 v[34:35], v[100:101], v[34:35]
	v_pk_add_f32 v[36:37], v[98:99], v[36:37]
	v_pk_mul_f32 v[70:71], v[150:151], v[38:39]
	v_pk_mul_f32 v[68:69], v[152:153], v[40:41]
	v_pk_mul_f32 v[98:99], v[154:155], v[34:35]
	v_pk_mul_f32 v[100:101], v[156:157], v[36:37]
	v_cvt_pk_bf16_f32 v68, v68, v69
	v_cvt_pk_bf16_f32 v69, v70, v71
	s_nop 0
	v_cvt_pk_bf16_f32 v70, v100, v101
	v_cvt_pk_bf16_f32 v71, v98, v99
	global_store_dwordx4 v[72:73], v[68:71], off
	global_load_dwordx4 v[68:71], v[186:187], off offset:512 nt
	s_nop 0
	global_load_dwordx4 v[98:101], v[186:187], off offset:528 nt
	v_lshl_add_u64 v[72:73], v[188:189], 0, v[148:149]
	v_lshlrev_b64 v[72:73], 1, v[72:73]
	v_cvt_pk_bf16_f32 v22, v22, v23
	v_cvt_pk_bf16_f32 v23, v24, v25
	v_cvt_pk_bf16_f32 v24, v18, v19
	v_cvt_pk_bf16_f32 v25, v20, v21
	v_lshl_add_u64 v[18:19], s[90:91], 0, v[72:73]
	global_store_dwordx4 v[18:19], v[22:25], off
	v_lshlrev_b32_e32 v20, 16, v24
	v_and_b32_e32 v21, 0xffff0000, v24
	v_lshlrev_b32_e32 v18, 16, v25
	v_and_b32_e32 v19, 0xffff0000, v25
	v_lshlrev_b32_e32 v24, 16, v22
	v_and_b32_e32 v25, 0xffff0000, v22
	v_lshlrev_b32_e32 v22, 16, v23
	v_and_b32_e32 v23, 0xffff0000, v23
	v_lshl_add_u64 v[72:73], s[96:97], 0, v[72:73]
	s_waitcnt vmcnt(2)
	v_pk_add_f32 v[22:23], v[70:71], v[22:23]
	v_pk_add_f32 v[24:25], v[68:69], v[24:25]
	s_waitcnt vmcnt(1)
	v_pk_add_f32 v[18:19], v[100:101], v[18:19]
	v_pk_add_f32 v[20:21], v[98:99], v[20:21]
	v_pk_mul_f32 v[70:71], v[150:151], v[22:23]
	v_pk_mul_f32 v[68:69], v[152:153], v[24:25]
	v_pk_mul_f32 v[98:99], v[154:155], v[18:19]
	v_pk_mul_f32 v[100:101], v[156:157], v[20:21]
	v_cvt_pk_bf16_f32 v68, v68, v69
	v_cvt_pk_bf16_f32 v69, v70, v71
	s_nop 0
	v_cvt_pk_bf16_f32 v70, v100, v101
	v_cvt_pk_bf16_f32 v71, v98, v99
	global_store_dwordx4 v[72:73], v[68:71], off
	global_load_dwordx4 v[68:71], v[190:191], off offset:512 nt
	s_nop 0
	global_load_dwordx4 v[98:101], v[190:191], off offset:528 nt
	v_lshl_add_u64 v[72:73], v[192:193], 0, v[148:149]
	v_lshlrev_b64 v[72:73], 1, v[72:73]
	v_cvt_pk_bf16_f32 v14, v14, v15
	v_cvt_pk_bf16_f32 v15, v16, v17
	v_cvt_pk_bf16_f32 v16, v10, v11
	v_cvt_pk_bf16_f32 v17, v12, v13
	v_lshl_add_u64 v[10:11], s[90:91], 0, v[72:73]
	global_store_dwordx4 v[10:11], v[14:17], off
	v_lshlrev_b32_e32 v12, 16, v16
	v_and_b32_e32 v13, 0xffff0000, v16
	v_lshlrev_b32_e32 v10, 16, v17
	v_and_b32_e32 v11, 0xffff0000, v17
	v_lshlrev_b32_e32 v16, 16, v14
	v_and_b32_e32 v17, 0xffff0000, v14
	v_lshlrev_b32_e32 v14, 16, v15
	v_and_b32_e32 v15, 0xffff0000, v15
	v_lshl_add_u64 v[72:73], s[96:97], 0, v[72:73]
	s_waitcnt vmcnt(2)
	v_pk_add_f32 v[14:15], v[70:71], v[14:15]
	v_pk_add_f32 v[16:17], v[68:69], v[16:17]
	s_waitcnt vmcnt(1)
	v_pk_add_f32 v[10:11], v[100:101], v[10:11]
	v_pk_add_f32 v[12:13], v[98:99], v[12:13]
	v_pk_mul_f32 v[70:71], v[150:151], v[14:15]
	v_pk_mul_f32 v[68:69], v[152:153], v[16:17]
	v_pk_mul_f32 v[98:99], v[154:155], v[10:11]
	v_pk_mul_f32 v[100:101], v[156:157], v[12:13]
	v_cvt_pk_bf16_f32 v68, v68, v69
	v_cvt_pk_bf16_f32 v69, v70, v71
	s_nop 0
	v_cvt_pk_bf16_f32 v70, v100, v101
	v_cvt_pk_bf16_f32 v71, v98, v99
	global_store_dwordx4 v[72:73], v[68:71], off
	global_load_dwordx4 v[68:71], v[194:195], off offset:512 nt
	s_nop 0
	global_load_dwordx4 v[98:101], v[194:195], off offset:528 nt
	v_lshl_add_u64 v[72:73], v[196:197], 0, v[148:149]
	v_lshlrev_b64 v[30:31], 1, v[72:73]
	v_cvt_pk_bf16_f32 v6, v6, v7
	v_cvt_pk_bf16_f32 v7, v8, v9
	v_cvt_pk_bf16_f32 v8, v2, v3
	v_cvt_pk_bf16_f32 v9, v4, v5
	v_lshl_add_u64 v[2:3], s[90:91], 0, v[30:31]
	global_store_dwordx4 v[2:3], v[6:9], off
	v_lshlrev_b32_e32 v4, 16, v8
	v_and_b32_e32 v5, 0xffff0000, v8
	v_lshlrev_b32_e32 v2, 16, v9
	v_and_b32_e32 v3, 0xffff0000, v9
	v_lshlrev_b32_e32 v8, 16, v6
	v_and_b32_e32 v9, 0xffff0000, v6
	v_lshlrev_b32_e32 v6, 16, v7
	v_and_b32_e32 v7, 0xffff0000, v7
	v_lshl_add_u64 v[30:31], s[96:97], 0, v[30:31]
	s_waitcnt vmcnt(2)
	v_pk_add_f32 v[8:9], v[68:69], v[8:9]
	v_pk_add_f32 v[6:7], v[70:71], v[6:7]
	v_pk_mul_f32 v[26:27], v[152:153], v[8:9]
	s_waitcnt vmcnt(1)
	v_pk_add_f32 v[2:3], v[100:101], v[2:3]
	v_pk_add_f32 v[4:5], v[98:99], v[4:5]
	v_pk_mul_f32 v[28:29], v[150:151], v[6:7]
	v_cvt_pk_bf16_f32 v26, v26, v27
	v_pk_mul_f32 v[32:33], v[154:155], v[2:3]
	v_cvt_pk_bf16_f32 v27, v28, v29
	v_pk_mul_f32 v[68:69], v[156:157], v[4:5]
	s_nop 0
	v_cvt_pk_bf16_f32 v28, v68, v69
	v_cvt_pk_bf16_f32 v29, v32, v33
	global_store_dwordx4 v[30:31], v[26:29], off
	s_nop 1
	v_and_b32_e32 v27, 64, v218
	v_xor_b32_e32 v26, 16, v218
	v_add_u32_e32 v27, 64, v27
	v_cmp_lt_i32_e32 vcc, v26, v27
	s_nop 1
	v_cndmask_b32_e32 v26, v218, v26, vcc
	v_lshlrev_b32_e32 v28, 2, v26
	v_xor_b32_e32 v26, 32, v218
	v_cmp_lt_i32_e32 vcc, v26, v27
	s_nop 1
	v_cndmask_b32_e32 v26, v218, v26, vcc
	v_lshlrev_b32_e32 v29, 2, v26
	ds_bpermute_b32 v26, v28, v66
	s_waitcnt lgkmcnt(0)
	v_add_f32_e32 v30, v66, v26
	ds_bpermute_b32 v31, v29, v30
	v_lshl_add_u64 v[26:27], v[146:147], 3, s[42:43]
	s_and_saveexec_b64 s[4:5], s[0:1]
	s_mov_b32 s8, 0x2f800000
	s_mov_b32 s9, 0xcf800000
	s_cbranch_execz .LBB0_558
	s_waitcnt lgkmcnt(0)
	v_add_f32_e32 v30, v30, v31
	v_mul_f32_e32 v30, 0x47800000, v30
	v_rndne_f32_e32 v30, v30
	v_mul_f32_e64 v31, |v30|, s8
	v_floor_f32_e32 v31, v31
	v_fma_f32 v32, v31, s9, |v30|
	v_cvt_u32_f32_e32 v32, v32
	v_cvt_u32_f32_e32 v31, v31
	v_ashrrev_i32_e32 v33, 31, v30
	v_xor_b32_e32 v30, v32, v33
	v_xor_b32_e32 v31, v31, v33
	v_sub_co_u32_e32 v30, vcc, v30, v33
	s_nop 1
	v_subb_co_u32_e32 v31, vcc, v31, v33, vcc
	global_atomic_add_x2 v[26:27], v[30:31], off

; #define PG8_STAGE(bufoff, gbase, voff) do { const char* gb_ = (const char*)(gbase); asm volatile("" : "+s"(gb_)); _Pragma("unroll") for (int _i = 0; _i < 2; ++_i) { unsigned vo_ = (voff)[_i]; asm volatile("" : "+v"(vo_));        \
;         __builtin_amdgcn_global_load_lds((const unsigned*)(gb_ + vo_), (PG8_LAS unsigned*)(lds + (bufoff) + ldsw + _i * 8192), 16, 0, 0); } } while (0)
; #define PG8_LDA(dst, b, h) do { _Pragma("unroll") for (int m = 0; m < 4; ++m) _Pragma("unroll") for (int k = 0; k < 2; ++k) dst[m][k] = *(const PG8_LAS bf16x8*)(lds + PG8_SA(b, h) + aoff + m * 2048 + k * 1024); } while (0)
; #define PG8_LDB(dst, b, h) do { _Pragma("unroll") for (int n = 0; n < 2; ++n) _Pragma("unroll") for (int k = 0; k < 2; ++k) dst[n][k] = *(const PG8_LAS bf16x8*)(lds + PG8_SB(b, h) + boff + n * 2048 + k * 1024); } while (0)
; #define PG8_MMA(ai, bj, At, Bt) do { __builtin_amdgcn_s_setprio(1); _Pragma("unroll") for (int m = 0; m < 4; ++m) _Pragma("unroll") for (int n = 0; n < 2; ++n) _Pragma("unroll") for (int k = 0; k < 2; ++k) \
;         acc[ai][bj][m][n] = __builtin_amdgcn_mfma_f32_16x16x32_bf16(Bt[n][k], At[m][k], acc[ai][bj][m][n], 0, 0, 0); __builtin_amdgcn_s_setprio(0); } while (0)
; #define PG8_WAIT_V(n) asm volatile("s_waitcnt vmcnt(" #n ")" ::: "memory")
; #define PG8_WAIT_L(n) asm volatile("s_waitcnt lgkmcnt(" #n ")" ::: "memory")
; template <class Epi, class Sched, bool ALIGN_EPI = false, bool SP2 = false>
; __device__ __forceinline__ void gemm_phase(PG8_LAS unsigned char* lds, const Gemm g, const Sched& S, const Epi& E) {
;     ...
;             const bool last = (t == nt - 2);
;             const char* a1 = cA + (size_t)(t + 1) * kstep;
;             const char* a2 = last ? nA : cA + (size_t)(t + 2) * kstep; const char* b2 = last ? nB : cB + (size_t)(t + 2) * kstep;
;             const char* a3 = a2 + kstep; const char* b3 = b2 + kstep;
;             if (last && has_next) S.a_ready(nxt);
;             if constexpr (SP2) {
;             PG8_LDB(B0, 0, 0); PG8_LDB(B1, 0, 1); PG8_SCHED; PG8_LDA(At, 0, 0); PG8_STAGE(PG8_SA(1, 1), a1 + hstep, voffA);
;             PG8_WAIT_V(8); PG8_WAIT_L(0); PG8_BAR; PG8_MMA(0, 0, At, B0); PG8_MMA(0, 1, At, B1); PG8_BAR; PG8_SCHED;
;             PG8_LDA(At, 0, 1); PG8_STAGE(PG8_SB(0, 0), b2, voffB); PG8_STAGE(PG8_SB(0, 1), b2 + hstep, voffB); PG8_STAGE(PG8_SA(0, 0), a2, voffA);
.LBB0_634:
	s_add_u32 s16, s14, 0x100
	s_addc_u32 s17, s15, 0
	s_cmp_eq_u32 s53, 28
	s_cselect_b32 s22, s49, s16
	s_cselect_b32 s23, s7, s17
	s_cselect_b32 s20, s50, s51
	s_cselect_b32 s21, s5, s52
	s_add_u32 s18, s22, 0x80
	s_addc_u32 s19, s23, 0
	s_add_i32 s54, 0, 0x10000
	s_add_i32 s55, 0, 0x14000
	ds_read_b128 v[82:85], v244
	ds_read_b128 v[86:89], v244 offset:1024
	ds_read_b128 v[90:93], v244 offset:2048
	ds_read_b128 v[94:97], v244 offset:3072
	ds_read_b128 v[146:149], v244 offset:16384
	ds_read_b128 v[150:153], v244 offset:17408
	ds_read_b128 v[154:157], v244 offset:18432
	ds_read_b128 v[158:161], v244 offset:19456
	s_add_u32 s14, s14, 0x80080
	s_addc_u32 s15, s15, 0
	ds_read_b128 v[178:181], v188
	ds_read_b128 v[190:193], v188 offset:1024
	ds_read_b128 v[194:197], v188 offset:2048
	ds_read_b128 v[198:201], v188 offset:3072
	ds_read_b128 v[202:205], v188 offset:4096
	ds_read_b128 v[206:209], v188 offset:5120
	ds_read_b128 v[210:213], v188 offset:6144
	ds_read_b128 v[220:223], v188 offset:7168
	s_add_i32 m0, s27, 0xc000
	s_nop 0
	global_load_lds_dwordx4 v1, s[14:15]
	s_add_i32 m0, s27, 0xe000
	s_nop 0
	global_load_lds_dwordx4 v164, s[14:15]
	s_waitcnt vmcnt(8)
	s_waitcnt lgkmcnt(0)
	s_barrier
	s_setprio 1
	s_waitcnt lgkmcnt(0)
	v_mfma_f32_16x16x32_bf16 v[142:145], v[82:85], v[178:181], v[142:145]
	v_mfma_f32_16x16x32_bf16 v[142:145], v[86:89], v[190:193], v[142:145]
	v_mfma_f32_16x16x32_bf16 v[126:129], v[82:85], v[194:197], v[126:129]
	v_mfma_f32_16x16x32_bf16 v[126:129], v[86:89], v[198:201], v[126:129]
	v_mfma_f32_16x16x32_bf16 v[110:113], v[82:85], v[202:205], v[110:113]
	v_mfma_f32_16x16x32_bf16 v[110:113], v[86:89], v[206:209], v[110:113]
	v_mfma_f32_16x16x32_bf16 v[78:81], v[82:85], v[210:213], v[78:81]
	v_mfma_f32_16x16x32_bf16 v[78:81], v[86:89], v[220:223], v[78:81]
	v_mfma_f32_16x16x32_bf16 v[138:141], v[90:93], v[178:181], v[138:141]
	v_mfma_f32_16x16x32_bf16 v[138:141], v[94:97], v[190:193], v[138:141]
	v_mfma_f32_16x16x32_bf16 v[122:125], v[90:93], v[194:197], v[122:125]
	v_mfma_f32_16x16x32_bf16 v[122:125], v[94:97], v[198:201], v[122:125]
	v_mfma_f32_16x16x32_bf16 v[106:109], v[90:93], v[202:205], v[106:109]
	v_mfma_f32_16x16x32_bf16 v[106:109], v[94:97], v[206:209], v[106:109]
	v_mfma_f32_16x16x32_bf16 v[74:77], v[90:93], v[210:213], v[74:77]
	v_mfma_f32_16x16x32_bf16 v[74:77], v[94:97], v[220:223], v[74:77]
	v_mfma_f32_16x16x32_bf16 v[134:137], v[146:149], v[178:181], v[134:137]
	v_mfma_f32_16x16x32_bf16 v[134:137], v[150:153], v[190:193], v[134:137]
	v_mfma_f32_16x16x32_bf16 v[118:121], v[146:149], v[194:197], v[118:121]
	v_mfma_f32_16x16x32_bf16 v[118:121], v[150:153], v[198:201], v[118:121]
	v_mfma_f32_16x16x32_bf16 v[102:105], v[146:149], v[202:205], v[102:105]
	v_mfma_f32_16x16x32_bf16 v[102:105], v[150:153], v[206:209], v[102:105]
	v_mfma_f32_16x16x32_bf16 v[70:73], v[146:149], v[210:213], v[70:73]
	v_mfma_f32_16x16x32_bf16 v[70:73], v[150:153], v[220:223], v[70:73]
	v_mfma_f32_16x16x32_bf16 v[130:133], v[154:157], v[178:181], v[130:133]
	v_mfma_f32_16x16x32_bf16 v[130:133], v[158:161], v[190:193], v[130:133]
	v_mfma_f32_16x16x32_bf16 v[114:117], v[154:157], v[194:197], v[114:117]
	v_mfma_f32_16x16x32_bf16 v[114:117], v[158:161], v[198:201], v[114:117]
	v_mfma_f32_16x16x32_bf16 v[98:101], v[154:157], v[202:205], v[98:101]
	v_mfma_f32_16x16x32_bf16 v[98:101], v[158:161], v[206:209], v[98:101]
	v_mfma_f32_16x16x32_bf16 v[66:69], v[154:157], v[210:213], v[66:69]
	v_mfma_f32_16x16x32_bf16 v[66:69], v[158:161], v[220:223], v[66:69]
	s_setprio 0
	s_barrier
	s_mov_b64 s[14:15], s[20:21]
	s_add_i32 s54, s54, s26
	ds_read_b128 v[178:181], v188 offset:16384
	ds_read_b128 v[190:193], v188 offset:17408
	ds_read_b128 v[194:197], v188 offset:18432
	ds_read_b128 v[198:201], v188 offset:19456
	ds_read_b128 v[202:205], v188 offset:20480
	ds_read_b128 v[206:209], v188 offset:21504
	ds_read_b128 v[210:213], v188 offset:22528
	ds_read_b128 v[220:223], v188 offset:23552
	s_mov_b32 m0, s54
	s_nop 0
	global_load_lds_dwordx4 v162, s[14:15]
	s_add_i32 m0, s54, 0x2000
	s_nop 0
	global_load_lds_dwordx4 v184, s[14:15]
	s_add_u32 s14, s20, 0x80000
	s_addc_u32 s15, s21, 0
	s_add_i32 s54, s55, s26
	s_mov_b32 m0, s54
	s_nop 0
	global_load_lds_dwordx4 v162, s[14:15]
	s_add_i32 m0, s54, 0x2000
	s_nop 0
	global_load_lds_dwordx4 v184, s[14:15]
	s_mov_b64 s[14:15], s[22:23]
	s_mov_b32 m0, s27
	s_nop 0
	global_load_lds_dwordx4 v1, s[14:15]
	s_mov_b32 m0, s28
	s_nop 0
	global_load_lds_dwordx4 v164, s[14:15]
	s_waitcnt vmcnt(8)
	s_waitcnt lgkmcnt(0)
	s_barrier
; #define PG8_STAGE(bufoff, gbase, voff) do { const char* gb_ = (const char*)(gbase); asm volatile("" : "+s"(gb_)); _Pragma("unroll") for (int _i = 0; _i < 2; ++_i) { unsigned vo_ = (voff)[_i]; asm volatile("" : "+v"(vo_));        \
;         __builtin_amdgcn_global_load_lds((const unsigned*)(gb_ + vo_), (PG8_LAS unsigned*)(lds + (bufoff) + ldsw + _i * 8192), 16, 0, 0); } } while (0)
; #define PG8_LDA(dst, b, h) do { _Pragma("unroll") for (int m = 0; m < 4; ++m) _Pragma("unroll") for (int k = 0; k < 2; ++k) dst[m][k] = *(const PG8_LAS bf16x8*)(lds + PG8_SA(b, h) + aoff + m * 2048 + k * 1024); } while (0)
; #define PG8_LDB(dst, b, h) do { _Pragma("unroll") for (int n = 0; n < 2; ++n) _Pragma("unroll") for (int k = 0; k < 2; ++k) dst[n][k] = *(const PG8_LAS bf16x8*)(lds + PG8_SB(b, h) + boff + n * 2048 + k * 1024); } while (0)
; #define PG8_MMA(ai, bj, At, Bt) do { __builtin_amdgcn_s_setprio(1); _Pragma("unroll") for (int m = 0; m < 4; ++m) _Pragma("unroll") for (int n = 0; n < 2; ++n) _Pragma("unroll") for (int k = 0; k < 2; ++k) \
;         acc[ai][bj][m][n] = __builtin_amdgcn_mfma_f32_16x16x32_bf16(Bt[n][k], At[m][k], acc[ai][bj][m][n], 0, 0, 0); __builtin_amdgcn_s_setprio(0); } while (0)
; #define PG8_WAIT_V(n) asm volatile("s_waitcnt vmcnt(" #n ")" ::: "memory")
; #define PG8_WAIT_L(n) asm volatile("s_waitcnt lgkmcnt(" #n ")" ::: "memory")
; #define PG8_BAR __builtin_amdgcn_s_barrier()
; #define PG8_SCHED __builtin_amdgcn_sched_barrier(0)
; template <class Epi, class Sched, bool ALIGN_EPI = false, bool SP2 = false>
; __device__ __forceinline__ void gemm_phase(PG8_LAS unsigned char* lds, const Gemm g, const Sched& S, const Epi& E) {
;     ...
;             PG8_WAIT_V(8); PG8_WAIT_L(0); PG8_BAR; PG8_MMA(1, 0, At, B0); PG8_MMA(1, 1, At, B1); PG8_BAR; PG8_SCHED;
;             PG8_LDB(B0, 1, 0); PG8_LDB(B1, 1, 1); PG8_SCHED; PG8_LDA(At, 1, 0); PG8_STAGE(PG8_SA(0, 1), a2 + hstep, voffA);
;             PG8_WAIT_V(8); PG8_WAIT_L(0); PG8_BAR; PG8_MMA(0, 0, At, B0); PG8_MMA(0, 1, At, B1); PG8_BAR; PG8_SCHED;
	s_setprio 1
	s_waitcnt lgkmcnt(0)
	v_mfma_f32_16x16x32_bf16 v[62:65], v[82:85], v[178:181], v[62:65]
	v_mfma_f32_16x16x32_bf16 v[62:65], v[86:89], v[190:193], v[62:65]
	v_mfma_f32_16x16x32_bf16 v[46:49], v[82:85], v[194:197], v[46:49]
	v_mfma_f32_16x16x32_bf16 v[46:49], v[86:89], v[198:201], v[46:49]
	v_mfma_f32_16x16x32_bf16 v[30:33], v[82:85], v[202:205], v[30:33]
	v_mfma_f32_16x16x32_bf16 v[30:33], v[86:89], v[206:209], v[30:33]
	v_mfma_f32_16x16x32_bf16 v[14:17], v[82:85], v[210:213], v[14:17]
	v_mfma_f32_16x16x32_bf16 v[14:17], v[86:89], v[220:223], v[14:17]
	v_mfma_f32_16x16x32_bf16 v[58:61], v[90:93], v[178:181], v[58:61]
	v_mfma_f32_16x16x32_bf16 v[58:61], v[94:97], v[190:193], v[58:61]
	v_mfma_f32_16x16x32_bf16 v[42:45], v[90:93], v[194:197], v[42:45]
	v_mfma_f32_16x16x32_bf16 v[42:45], v[94:97], v[198:201], v[42:45]
	v_mfma_f32_16x16x32_bf16 v[26:29], v[90:93], v[202:205], v[26:29]
	v_mfma_f32_16x16x32_bf16 v[26:29], v[94:97], v[206:209], v[26:29]
	v_mfma_f32_16x16x32_bf16 v[10:13], v[90:93], v[210:213], v[10:13]
	v_mfma_f32_16x16x32_bf16 v[10:13], v[94:97], v[220:223], v[10:13]
	v_mfma_f32_16x16x32_bf16 v[54:57], v[146:149], v[178:181], v[54:57]
	v_mfma_f32_16x16x32_bf16 v[54:57], v[150:153], v[190:193], v[54:57]
	v_mfma_f32_16x16x32_bf16 v[38:41], v[146:149], v[194:197], v[38:41]
	v_mfma_f32_16x16x32_bf16 v[38:41], v[150:153], v[198:201], v[38:41]
	v_mfma_f32_16x16x32_bf16 v[22:25], v[146:149], v[202:205], v[22:25]
	v_mfma_f32_16x16x32_bf16 v[22:25], v[150:153], v[206:209], v[22:25]
	v_mfma_f32_16x16x32_bf16 v[6:9], v[146:149], v[210:213], v[6:9]
	v_mfma_f32_16x16x32_bf16 v[6:9], v[150:153], v[220:223], v[6:9]
	v_mfma_f32_16x16x32_bf16 v[50:53], v[154:157], v[178:181], v[50:53]
	v_mfma_f32_16x16x32_bf16 v[50:53], v[158:161], v[190:193], v[50:53]
	v_mfma_f32_16x16x32_bf16 v[34:37], v[154:157], v[194:197], v[34:37]
	v_mfma_f32_16x16x32_bf16 v[34:37], v[158:161], v[198:201], v[34:37]
	v_mfma_f32_16x16x32_bf16 v[18:21], v[154:157], v[202:205], v[18:21]
	v_mfma_f32_16x16x32_bf16 v[18:21], v[158:161], v[206:209], v[18:21]
	v_mfma_f32_16x16x32_bf16 v[2:5], v[154:157], v[210:213], v[2:5]
	v_mfma_f32_16x16x32_bf16 v[2:5], v[158:161], v[220:223], v[2:5]
	s_setprio 0
	s_barrier
	s_add_i32 s54, 0, 0x18000
	s_add_i32 s55, 0, 0x1c000
	ds_read_b128 v[82:85], v244 offset:32768
	ds_read_b128 v[86:89], v244 offset:33792
	ds_read_b128 v[90:93], v244 offset:34816
	ds_read_b128 v[94:97], v244 offset:35840
	ds_read_b128 v[146:149], v244 offset:49152
	ds_read_b128 v[150:153], v244 offset:50176
	ds_read_b128 v[154:157], v244 offset:51200
	ds_read_b128 v[158:161], v244 offset:52224
	s_add_u32 s14, s22, 0x80000
	s_addc_u32 s15, s23, 0
	s_mov_b32 m0, s29
	ds_read_b128 v[178:181], v188 offset:32768
	ds_read_b128 v[190:193], v188 offset:33792
	ds_read_b128 v[194:197], v188 offset:34816
	ds_read_b128 v[198:201], v188 offset:35840
	ds_read_b128 v[202:205], v188 offset:36864
	ds_read_b128 v[206:209], v188 offset:37888
	ds_read_b128 v[210:213], v188 offset:38912
	ds_read_b128 v[220:223], v188 offset:39936
	s_nop 0
	global_load_lds_dwordx4 v1, s[14:15]
	s_mov_b32 m0, s33
	s_nop 0
	global_load_lds_dwordx4 v164, s[14:15]
	s_waitcnt vmcnt(8)
	s_waitcnt lgkmcnt(0)
	s_barrier
	s_setprio 1
	s_waitcnt lgkmcnt(0)
	v_mfma_f32_16x16x32_bf16 v[142:145], v[82:85], v[178:181], v[142:145]
	v_mfma_f32_16x16x32_bf16 v[142:145], v[86:89], v[190:193], v[142:145]
	v_mfma_f32_16x16x32_bf16 v[126:129], v[82:85], v[194:197], v[126:129]
	v_mfma_f32_16x16x32_bf16 v[126:129], v[86:89], v[198:201], v[126:129]
	v_mfma_f32_16x16x32_bf16 v[110:113], v[82:85], v[202:205], v[110:113]
	v_mfma_f32_16x16x32_bf16 v[110:113], v[86:89], v[206:209], v[110:113]
	v_mfma_f32_16x16x32_bf16 v[78:81], v[82:85], v[210:213], v[78:81]
	v_mfma_f32_16x16x32_bf16 v[78:81], v[86:89], v[220:223], v[78:81]
	v_mfma_f32_16x16x32_bf16 v[138:141], v[90:93], v[178:181], v[138:141]
	v_mfma_f32_16x16x32_bf16 v[138:141], v[94:97], v[190:193], v[138:141]
	v_mfma_f32_16x16x32_bf16 v[122:125], v[90:93], v[194:197], v[122:125]
	v_mfma_f32_16x16x32_bf16 v[122:125], v[94:97], v[198:201], v[122:125]
	v_mfma_f32_16x16x32_bf16 v[106:109], v[90:93], v[202:205], v[106:109]
	v_mfma_f32_16x16x32_bf16 v[106:109], v[94:97], v[206:209], v[106:109]
	v_mfma_f32_16x16x32_bf16 v[74:77], v[90:93], v[210:213], v[74:77]
	v_mfma_f32_16x16x32_bf16 v[74:77], v[94:97], v[220:223], v[74:77]
	v_mfma_f32_16x16x32_bf16 v[134:137], v[146:149], v[178:181], v[134:137]
	v_mfma_f32_16x16x32_bf16 v[134:137], v[150:153], v[190:193], v[134:137]
	v_mfma_f32_16x16x32_bf16 v[118:121], v[146:149], v[194:197], v[118:121]
	v_mfma_f32_16x16x32_bf16 v[118:121], v[150:153], v[198:201], v[118:121]
	v_mfma_f32_16x16x32_bf16 v[102:105], v[146:149], v[202:205], v[102:105]
	v_mfma_f32_16x16x32_bf16 v[102:105], v[150:153], v[206:209], v[102:105]
	v_mfma_f32_16x16x32_bf16 v[70:73], v[146:149], v[210:213], v[70:73]
	v_mfma_f32_16x16x32_bf16 v[70:73], v[150:153], v[220:223], v[70:73]
	v_mfma_f32_16x16x32_bf16 v[130:133], v[154:157], v[178:181], v[130:133]
	v_mfma_f32_16x16x32_bf16 v[130:133], v[158:161], v[190:193], v[130:133]
	v_mfma_f32_16x16x32_bf16 v[114:117], v[154:157], v[194:197], v[114:117]
	v_mfma_f32_16x16x32_bf16 v[114:117], v[158:161], v[198:201], v[114:117]
	v_mfma_f32_16x16x32_bf16 v[98:101], v[154:157], v[202:205], v[98:101]
	v_mfma_f32_16x16x32_bf16 v[98:101], v[158:161], v[206:209], v[98:101]
	v_mfma_f32_16x16x32_bf16 v[66:69], v[154:157], v[210:213], v[66:69]
	v_mfma_f32_16x16x32_bf16 v[66:69], v[158:161], v[220:223], v[66:69]
	s_setprio 0
	s_barrier
; #define PG8_STAGE(bufoff, gbase, voff) do { const char* gb_ = (const char*)(gbase); asm volatile("" : "+s"(gb_)); _Pragma("unroll") for (int _i = 0; _i < 2; ++_i) { unsigned vo_ = (voff)[_i]; asm volatile("" : "+v"(vo_));        \
;         __builtin_amdgcn_global_load_lds((const unsigned*)(gb_ + vo_), (PG8_LAS unsigned*)(lds + (bufoff) + ldsw + _i * 8192), 16, 0, 0); } } while (0)
; #define PG8_LDA(dst, b, h) do { _Pragma("unroll") for (int m = 0; m < 4; ++m) _Pragma("unroll") for (int k = 0; k < 2; ++k) dst[m][k] = *(const PG8_LAS bf16x8*)(lds + PG8_SA(b, h) + aoff + m * 2048 + k * 1024); } while (0)
; #define PG8_MMA(ai, bj, At, Bt) do { __builtin_amdgcn_s_setprio(1); _Pragma("unroll") for (int m = 0; m < 4; ++m) _Pragma("unroll") for (int n = 0; n < 2; ++n) _Pragma("unroll") for (int k = 0; k < 2; ++k) \
;         acc[ai][bj][m][n] = __builtin_amdgcn_mfma_f32_16x16x32_bf16(Bt[n][k], At[m][k], acc[ai][bj][m][n], 0, 0, 0); __builtin_amdgcn_s_setprio(0); } while (0)
; #define PG8_WAIT_V(n) asm volatile("s_waitcnt vmcnt(" #n ")" ::: "memory")
; #define PG8_WAIT_L(n) asm volatile("s_waitcnt lgkmcnt(" #n ")" ::: "memory")
; #define PG8_BAR __builtin_amdgcn_s_barrier()
; #define PG8_SCHED __builtin_amdgcn_sched_barrier(0)
; template <class Epi, class Sched, bool ALIGN_EPI = false, bool SP2 = false>
; __device__ __forceinline__ void gemm_phase(PG8_LAS unsigned char* lds, const Gemm g, const Sched& S, const Epi& E) {
;     ...
;             PG8_LDA(At, 1, 1); PG8_STAGE(PG8_SB(1, 0), b3, voffB); PG8_STAGE(PG8_SB(1, 1), b3 + hstep, voffB); PG8_STAGE(PG8_SA(1, 0), a3, voffA);
;             PG8_WAIT_V(8); PG8_WAIT_L(0); PG8_BAR; PG8_MMA(1, 0, At, B0); PG8_MMA(1, 1, At, B1); PG8_BAR; PG8_SCHED;
;     ...
;         if constexpr (ALIGN_EPI) { if (wr == 0) PG8_BAR; }
	s_add_u32 s14, s20, 0x80
	s_addc_u32 s15, s21, 0
	s_add_i32 s22, s54, s26
	ds_read_b128 v[178:181], v188 offset:49152
	ds_read_b128 v[190:193], v188 offset:50176
	ds_read_b128 v[194:197], v188 offset:51200
	ds_read_b128 v[198:201], v188 offset:52224
	ds_read_b128 v[202:205], v188 offset:53248
	ds_read_b128 v[206:209], v188 offset:54272
	ds_read_b128 v[210:213], v188 offset:55296
	ds_read_b128 v[220:223], v188 offset:56320
	s_mov_b32 m0, s22
	s_nop 0
	global_load_lds_dwordx4 v162, s[14:15]
	s_add_i32 m0, s22, 0x2000
	s_nop 0
	global_load_lds_dwordx4 v184, s[14:15]
	s_add_u32 s14, s20, 0x80080
	s_addc_u32 s15, s21, 0
	s_add_i32 s20, s55, s26
	s_mov_b32 m0, s20
	s_nop 0
	global_load_lds_dwordx4 v162, s[14:15]
	s_add_i32 m0, s20, 0x2000
	s_nop 0
	global_load_lds_dwordx4 v184, s[14:15]
	s_mov_b32 m0, s38
	s_nop 0
	global_load_lds_dwordx4 v1, s[18:19]
	s_mov_b32 m0, s39
	s_nop 0
	global_load_lds_dwordx4 v164, s[18:19]
	s_waitcnt vmcnt(8)
	s_waitcnt lgkmcnt(0)
	s_barrier
	s_setprio 1
	s_waitcnt lgkmcnt(0)
	v_mfma_f32_16x16x32_bf16 v[62:65], v[82:85], v[178:181], v[62:65]
	v_mfma_f32_16x16x32_bf16 v[62:65], v[86:89], v[190:193], v[62:65]
	v_mfma_f32_16x16x32_bf16 v[46:49], v[82:85], v[194:197], v[46:49]
	v_mfma_f32_16x16x32_bf16 v[46:49], v[86:89], v[198:201], v[46:49]
	v_mfma_f32_16x16x32_bf16 v[30:33], v[82:85], v[202:205], v[30:33]
	v_mfma_f32_16x16x32_bf16 v[30:33], v[86:89], v[206:209], v[30:33]
	v_mfma_f32_16x16x32_bf16 v[14:17], v[82:85], v[210:213], v[14:17]
	v_mfma_f32_16x16x32_bf16 v[14:17], v[86:89], v[220:223], v[14:17]
	v_mfma_f32_16x16x32_bf16 v[58:61], v[90:93], v[178:181], v[58:61]
	v_mfma_f32_16x16x32_bf16 v[58:61], v[94:97], v[190:193], v[58:61]
	v_mfma_f32_16x16x32_bf16 v[42:45], v[90:93], v[194:197], v[42:45]
	v_mfma_f32_16x16x32_bf16 v[42:45], v[94:97], v[198:201], v[42:45]
	v_mfma_f32_16x16x32_bf16 v[26:29], v[90:93], v[202:205], v[26:29]
	v_mfma_f32_16x16x32_bf16 v[26:29], v[94:97], v[206:209], v[26:29]
	v_mfma_f32_16x16x32_bf16 v[10:13], v[90:93], v[210:213], v[10:13]
	v_mfma_f32_16x16x32_bf16 v[10:13], v[94:97], v[220:223], v[10:13]
	v_mfma_f32_16x16x32_bf16 v[54:57], v[146:149], v[178:181], v[54:57]
	v_mfma_f32_16x16x32_bf16 v[54:57], v[150:153], v[190:193], v[54:57]
	v_mfma_f32_16x16x32_bf16 v[38:41], v[146:149], v[194:197], v[38:41]
	v_mfma_f32_16x16x32_bf16 v[38:41], v[150:153], v[198:201], v[38:41]
	v_mfma_f32_16x16x32_bf16 v[22:25], v[146:149], v[202:205], v[22:25]
	v_mfma_f32_16x16x32_bf16 v[22:25], v[150:153], v[206:209], v[22:25]
	v_mfma_f32_16x16x32_bf16 v[6:9], v[146:149], v[210:213], v[6:9]
	v_mfma_f32_16x16x32_bf16 v[6:9], v[150:153], v[220:223], v[6:9]
	v_mfma_f32_16x16x32_bf16 v[50:53], v[154:157], v[178:181], v[50:53]
	v_mfma_f32_16x16x32_bf16 v[50:53], v[158:161], v[190:193], v[50:53]
	v_mfma_f32_16x16x32_bf16 v[34:37], v[154:157], v[194:197], v[34:37]
	v_mfma_f32_16x16x32_bf16 v[34:37], v[158:161], v[198:201], v[34:37]
	v_mfma_f32_16x16x32_bf16 v[18:21], v[154:157], v[202:205], v[18:21]
	v_mfma_f32_16x16x32_bf16 v[18:21], v[158:161], v[206:209], v[18:21]
	v_mfma_f32_16x16x32_bf16 v[2:5], v[154:157], v[210:213], v[2:5]
	v_mfma_f32_16x16x32_bf16 v[2:5], v[158:161], v[220:223], v[2:5]
	s_setprio 0
	s_barrier
	s_add_i32 s53, s53, 2
	s_add_u32 s51, s51, 0x100
	s_addc_u32 s52, s52, 0
	s_cmp_gt_u32 s53, 29
	s_mov_b64 s[14:15], s[16:17]
	s_cbranch_scc0 .LBB0_634
	s_and_b64 vcc, exec, s[2:3]
	s_cbranch_vccz .LBB0_637
	s_barrier

; #define PG8_STAGE(bufoff, gbase, voff) do { const char* gb_ = (const char*)(gbase); asm volatile("" : "+s"(gb_)); _Pragma("unroll") for (int _i = 0; _i < 2; ++_i) { unsigned vo_ = (voff)[_i]; asm volatile("" : "+v"(vo_));        \
;         __builtin_amdgcn_global_load_lds((const unsigned*)(gb_ + vo_), (PG8_LAS unsigned*)(lds + (bufoff) + ldsw + _i * 8192), 16, 0, 0); } } while (0)
; #define PG8_LDA(dst, b, h) do { _Pragma("unroll") for (int m = 0; m < 4; ++m) _Pragma("unroll") for (int k = 0; k < 2; ++k) dst[m][k] = *(const PG8_LAS bf16x8*)(lds + PG8_SA(b, h) + aoff + m * 2048 + k * 1024); } while (0)
; #define PG8_LDB(dst, b, h) do { _Pragma("unroll") for (int n = 0; n < 2; ++n) _Pragma("unroll") for (int k = 0; k < 2; ++k) dst[n][k] = *(const PG8_LAS bf16x8*)(lds + PG8_SB(b, h) + boff + n * 2048 + k * 1024); } while (0)
; #define PG8_MMA(ai, bj, At, Bt) do { __builtin_amdgcn_s_setprio(1); _Pragma("unroll") for (int m = 0; m < 4; ++m) _Pragma("unroll") for (int n = 0; n < 2; ++n) _Pragma("unroll") for (int k = 0; k < 2; ++k) \
;         acc[ai][bj][m][n] = __builtin_amdgcn_mfma_f32_16x16x32_bf16(Bt[n][k], At[m][k], acc[ai][bj][m][n], 0, 0, 0); __builtin_amdgcn_s_setprio(0); } while (0)
; #define PG8_WAIT_V(n) asm volatile("s_waitcnt vmcnt(" #n ")" ::: "memory")
; template <class Epi, class Sched, bool ALIGN_EPI = false, bool SP2 = false>
; __device__ __forceinline__ void gemm_phase(PG8_LAS unsigned char* lds, const Gemm g, const Sched& S, const Epi& E) {
;     ...
;             const bool last = (t == nt - 2);
;             const char* a1 = cA + (size_t)(t + 1) * kstep;
;             const char* a2 = last ? nA : cA + (size_t)(t + 2) * kstep; const char* b2 = last ? nB : cB + (size_t)(t + 2) * kstep;
;             const char* a3 = a2 + kstep; const char* b3 = b2 + kstep;
;             if (last && has_next) S.a_ready(nxt);
;             if constexpr (SP2) {
;             PG8_LDB(B0, 0, 0); PG8_LDB(B1, 0, 1); PG8_SCHED; PG8_LDA(At, 0, 0); PG8_STAGE(PG8_SA(1, 1), a1 + hstep, voffA);
;             PG8_WAIT_V(8); PG8_WAIT_L(0); PG8_BAR; PG8_MMA(0, 0, At, B0); PG8_MMA(0, 1, At, B1); PG8_BAR; PG8_SCHED;
;             PG8_LDA(At, 0, 1); PG8_STAGE(PG8_SB(0, 0), b2, voffB); PG8_STAGE(PG8_SB(0, 1), b2 + hstep, voffB); PG8_STAGE(PG8_SA(0, 0), a2, voffA);
;             PG8_WAIT_V(8); PG8_WAIT_L(0); PG8_BAR; PG8_MMA(1, 0, At, B0); PG8_MMA(1, 1, At, B1); PG8_BAR; PG8_SCHED;
.LBB0_707:
	s_add_u32 s2, s4, 0x100
	s_addc_u32 s3, s5, 0
	s_cmpk_eq_i32 s35, 0x54
	s_cselect_b32 s10, s52, s2
	s_cselect_b32 s11, s53, s3
	s_cselect_b32 s8, s42, s31
	s_cselect_b32 s9, s43, s34
	s_add_u32 s6, s10, 0x80
	s_addc_u32 s7, s11, 0
	s_add_i32 s38, 0, 0x10000
	s_add_i32 s39, 0, 0x14000
	ds_read_b128 v[34:37], v244
	ds_read_b128 v[38:41], v244 offset:1024
	ds_read_b128 v[98:101], v244 offset:2048
	ds_read_b128 v[102:105], v244 offset:3072
	ds_read_b128 v[146:149], v244 offset:16384
	ds_read_b128 v[150:153], v244 offset:17408
	ds_read_b128 v[154:157], v244 offset:18432
	ds_read_b128 v[158:161], v244 offset:19456
	s_add_u32 s4, s4, 0x160080
	s_addc_u32 s5, s5, 0
	ds_read_b128 v[178:181], v194
	ds_read_b128 v[182:185], v194 offset:1024
	ds_read_b128 v[186:189], v194 offset:2048
	ds_read_b128 v[196:199], v194 offset:3072
	ds_read_b128 v[200:203], v194 offset:4096
	ds_read_b128 v[204:207], v194 offset:5120
	ds_read_b128 v[208:211], v194 offset:6144
	ds_read_b128 v[212:215], v194 offset:7168
	s_add_i32 m0, s16, 0xc000
	s_nop 0
	global_load_lds_dwordx4 v1, s[4:5]
	s_add_i32 m0, s16, 0xe000
	s_nop 0
	global_load_lds_dwordx4 v164, s[4:5]
	s_waitcnt vmcnt(8)
	s_waitcnt lgkmcnt(0)
	s_barrier
	s_setprio 1
	s_waitcnt lgkmcnt(0)
	v_mfma_f32_16x16x32_bf16 v[142:145], v[34:37], v[178:181], v[142:145]
	v_mfma_f32_16x16x32_bf16 v[142:145], v[38:41], v[182:185], v[142:145]
	v_mfma_f32_16x16x32_bf16 v[134:137], v[34:37], v[186:189], v[134:137]
	v_mfma_f32_16x16x32_bf16 v[134:137], v[38:41], v[196:199], v[134:137]
	v_mfma_f32_16x16x32_bf16 v[126:129], v[34:37], v[200:203], v[126:129]
	v_mfma_f32_16x16x32_bf16 v[126:129], v[38:41], v[204:207], v[126:129]
	v_mfma_f32_16x16x32_bf16 v[118:121], v[34:37], v[208:211], v[118:121]
	v_mfma_f32_16x16x32_bf16 v[118:121], v[38:41], v[212:215], v[118:121]
	v_mfma_f32_16x16x32_bf16 v[138:141], v[98:101], v[178:181], v[138:141]
	v_mfma_f32_16x16x32_bf16 v[138:141], v[102:105], v[182:185], v[138:141]
	v_mfma_f32_16x16x32_bf16 v[130:133], v[98:101], v[186:189], v[130:133]
	v_mfma_f32_16x16x32_bf16 v[130:133], v[102:105], v[196:199], v[130:133]
	v_mfma_f32_16x16x32_bf16 v[122:125], v[98:101], v[200:203], v[122:125]
	v_mfma_f32_16x16x32_bf16 v[122:125], v[102:105], v[204:207], v[122:125]
	v_mfma_f32_16x16x32_bf16 v[114:117], v[98:101], v[208:211], v[114:117]
	v_mfma_f32_16x16x32_bf16 v[114:117], v[102:105], v[212:215], v[114:117]
	v_mfma_f32_16x16x32_bf16 v[70:73], v[146:149], v[178:181], v[70:73]
	v_mfma_f32_16x16x32_bf16 v[70:73], v[150:153], v[182:185], v[70:73]
	v_mfma_f32_16x16x32_bf16 v[62:65], v[146:149], v[186:189], v[62:65]
	v_mfma_f32_16x16x32_bf16 v[62:65], v[150:153], v[196:199], v[62:65]
	v_mfma_f32_16x16x32_bf16 v[54:57], v[146:149], v[200:203], v[54:57]
	v_mfma_f32_16x16x32_bf16 v[54:57], v[150:153], v[204:207], v[54:57]
	v_mfma_f32_16x16x32_bf16 v[46:49], v[146:149], v[208:211], v[46:49]
	v_mfma_f32_16x16x32_bf16 v[46:49], v[150:153], v[212:215], v[46:49]
	v_mfma_f32_16x16x32_bf16 v[66:69], v[154:157], v[178:181], v[66:69]
	v_mfma_f32_16x16x32_bf16 v[66:69], v[158:161], v[182:185], v[66:69]
	v_mfma_f32_16x16x32_bf16 v[58:61], v[154:157], v[186:189], v[58:61]
	v_mfma_f32_16x16x32_bf16 v[58:61], v[158:161], v[196:199], v[58:61]
	v_mfma_f32_16x16x32_bf16 v[50:53], v[154:157], v[200:203], v[50:53]
	v_mfma_f32_16x16x32_bf16 v[50:53], v[158:161], v[204:207], v[50:53]
	v_mfma_f32_16x16x32_bf16 v[42:45], v[154:157], v[208:211], v[42:45]
	v_mfma_f32_16x16x32_bf16 v[42:45], v[158:161], v[212:215], v[42:45]
	s_setprio 0
	s_barrier
	s_mov_b64 s[4:5], s[8:9]
	s_add_i32 s38, s38, s15
	ds_read_b128 v[178:181], v194 offset:16384
	ds_read_b128 v[182:185], v194 offset:17408
	ds_read_b128 v[186:189], v194 offset:18432
	ds_read_b128 v[196:199], v194 offset:19456
	ds_read_b128 v[200:203], v194 offset:20480
	ds_read_b128 v[204:207], v194 offset:21504
	ds_read_b128 v[208:211], v194 offset:22528
	ds_read_b128 v[212:215], v194 offset:23552
	s_mov_b32 m0, s38
	s_nop 0
	global_load_lds_dwordx4 v162, s[4:5]
	s_add_i32 m0, s38, 0x2000
	s_nop 0
	global_load_lds_dwordx4 v190, s[4:5]
	s_add_u32 s4, s8, 0x160000
	s_addc_u32 s5, s9, 0
	s_add_i32 s38, s39, s15
	s_mov_b32 m0, s38
	s_nop 0
	global_load_lds_dwordx4 v162, s[4:5]
	s_add_i32 m0, s38, 0x2000
	s_nop 0
	global_load_lds_dwordx4 v190, s[4:5]
	s_mov_b64 s[4:5], s[10:11]
	s_mov_b32 m0, s16
	s_nop 0
	global_load_lds_dwordx4 v1, s[4:5]
	s_mov_b32 m0, s17
	s_nop 0
	global_load_lds_dwordx4 v164, s[4:5]
	s_waitcnt vmcnt(8)
	s_waitcnt lgkmcnt(0)
	s_barrier
	s_setprio 1
	s_waitcnt lgkmcnt(0)
	v_mfma_f32_16x16x32_bf16 v[110:113], v[34:37], v[178:181], v[110:113]
	v_mfma_f32_16x16x32_bf16 v[110:113], v[38:41], v[182:185], v[110:113]
	v_mfma_f32_16x16x32_bf16 v[94:97], v[34:37], v[186:189], v[94:97]
	v_mfma_f32_16x16x32_bf16 v[94:97], v[38:41], v[196:199], v[94:97]
	v_mfma_f32_16x16x32_bf16 v[86:89], v[34:37], v[200:203], v[86:89]
	v_mfma_f32_16x16x32_bf16 v[86:89], v[38:41], v[204:207], v[86:89]
	v_mfma_f32_16x16x32_bf16 v[34:37], v[34:37], v[208:211], v[78:81]
	v_mfma_f32_16x16x32_bf16 v[34:37], v[38:41], v[212:215], v[34:37]
	v_mfma_f32_16x16x32_bf16 v[106:109], v[98:101], v[178:181], v[106:109]
	v_mfma_f32_16x16x32_bf16 v[106:109], v[102:105], v[182:185], v[106:109]
	v_mfma_f32_16x16x32_bf16 v[90:93], v[98:101], v[186:189], v[90:93]
	v_mfma_f32_16x16x32_bf16 v[90:93], v[102:105], v[196:199], v[90:93]
	v_mfma_f32_16x16x32_bf16 v[82:85], v[98:101], v[200:203], v[82:85]
	v_mfma_f32_16x16x32_bf16 v[82:85], v[102:105], v[204:207], v[82:85]
	v_mfma_f32_16x16x32_bf16 v[38:41], v[98:101], v[208:211], v[74:77]
	v_mfma_f32_16x16x32_bf16 v[38:41], v[102:105], v[212:215], v[38:41]
	v_mfma_f32_16x16x32_bf16 v[30:33], v[146:149], v[178:181], v[30:33]
	v_mfma_f32_16x16x32_bf16 v[30:33], v[150:153], v[182:185], v[30:33]
	v_mfma_f32_16x16x32_bf16 v[22:25], v[146:149], v[186:189], v[22:25]
	v_mfma_f32_16x16x32_bf16 v[22:25], v[150:153], v[196:199], v[22:25]
	v_mfma_f32_16x16x32_bf16 v[14:17], v[146:149], v[200:203], v[14:17]
	v_mfma_f32_16x16x32_bf16 v[14:17], v[150:153], v[204:207], v[14:17]
	v_mfma_f32_16x16x32_bf16 v[6:9], v[146:149], v[208:211], v[6:9]
	v_mfma_f32_16x16x32_bf16 v[6:9], v[150:153], v[212:215], v[6:9]
	v_mfma_f32_16x16x32_bf16 v[26:29], v[154:157], v[178:181], v[26:29]
	v_mfma_f32_16x16x32_bf16 v[26:29], v[158:161], v[182:185], v[26:29]
	v_mfma_f32_16x16x32_bf16 v[18:21], v[154:157], v[186:189], v[18:21]
	v_mfma_f32_16x16x32_bf16 v[18:21], v[158:161], v[196:199], v[18:21]
	v_mfma_f32_16x16x32_bf16 v[10:13], v[154:157], v[200:203], v[10:13]
	v_mfma_f32_16x16x32_bf16 v[10:13], v[158:161], v[204:207], v[10:13]
	v_mfma_f32_16x16x32_bf16 v[2:5], v[154:157], v[208:211], v[2:5]
	v_mfma_f32_16x16x32_bf16 v[2:5], v[158:161], v[212:215], v[2:5]
	s_setprio 0
	s_barrier
; #define PG8_STAGE(bufoff, gbase, voff) do { const char* gb_ = (const char*)(gbase); asm volatile("" : "+s"(gb_)); _Pragma("unroll") for (int _i = 0; _i < 2; ++_i) { unsigned vo_ = (voff)[_i]; asm volatile("" : "+v"(vo_));        \
;         __builtin_amdgcn_global_load_lds((const unsigned*)(gb_ + vo_), (PG8_LAS unsigned*)(lds + (bufoff) + ldsw + _i * 8192), 16, 0, 0); } } while (0)
; #define PG8_LDA(dst, b, h) do { _Pragma("unroll") for (int m = 0; m < 4; ++m) _Pragma("unroll") for (int k = 0; k < 2; ++k) dst[m][k] = *(const PG8_LAS bf16x8*)(lds + PG8_SA(b, h) + aoff + m * 2048 + k * 1024); } while (0)
; #define PG8_LDB(dst, b, h) do { _Pragma("unroll") for (int n = 0; n < 2; ++n) _Pragma("unroll") for (int k = 0; k < 2; ++k) dst[n][k] = *(const PG8_LAS bf16x8*)(lds + PG8_SB(b, h) + boff + n * 2048 + k * 1024); } while (0)
; #define PG8_MMA(ai, bj, At, Bt) do { __builtin_amdgcn_s_setprio(1); _Pragma("unroll") for (int m = 0; m < 4; ++m) _Pragma("unroll") for (int n = 0; n < 2; ++n) _Pragma("unroll") for (int k = 0; k < 2; ++k) \
;         acc[ai][bj][m][n] = __builtin_amdgcn_mfma_f32_16x16x32_bf16(Bt[n][k], At[m][k], acc[ai][bj][m][n], 0, 0, 0); __builtin_amdgcn_s_setprio(0); } while (0)
; #define PG8_WAIT_V(n) asm volatile("s_waitcnt vmcnt(" #n ")" ::: "memory")
; #define PG8_WAIT_L(n) asm volatile("s_waitcnt lgkmcnt(" #n ")" ::: "memory")
; #define PG8_BAR __builtin_amdgcn_s_barrier()
; #define PG8_SCHED __builtin_amdgcn_sched_barrier(0)
; template <class Epi, class Sched, bool ALIGN_EPI = false, bool SP2 = false>
; __device__ __forceinline__ void gemm_phase(PG8_LAS unsigned char* lds, const Gemm g, const Sched& S, const Epi& E) {
;     ...
;             PG8_LDB(B0, 1, 0); PG8_LDB(B1, 1, 1); PG8_SCHED; PG8_LDA(At, 1, 0); PG8_STAGE(PG8_SA(0, 1), a2 + hstep, voffA);
;             PG8_WAIT_V(8); PG8_WAIT_L(0); PG8_BAR; PG8_MMA(0, 0, At, B0); PG8_MMA(0, 1, At, B1); PG8_BAR; PG8_SCHED;
;             PG8_LDA(At, 1, 1); PG8_STAGE(PG8_SB(1, 0), b3, voffB); PG8_STAGE(PG8_SB(1, 1), b3 + hstep, voffB); PG8_STAGE(PG8_SA(1, 0), a3, voffA);
;             PG8_WAIT_V(8); PG8_WAIT_L(0); PG8_BAR; PG8_MMA(1, 0, At, B0); PG8_MMA(1, 1, At, B1); PG8_BAR; PG8_SCHED;
	s_add_i32 s38, 0, 0x18000
	s_add_i32 s39, 0, 0x1c000
	ds_read_b128 v[74:77], v244 offset:32768
	ds_read_b128 v[78:81], v244 offset:33792
	ds_read_b128 v[98:101], v244 offset:34816
	ds_read_b128 v[102:105], v244 offset:35840
	ds_read_b128 v[146:149], v244 offset:49152
	ds_read_b128 v[150:153], v244 offset:50176
	ds_read_b128 v[154:157], v244 offset:51200
	ds_read_b128 v[158:161], v244 offset:52224
	s_add_u32 s4, s10, 0x160000
	s_addc_u32 s5, s11, 0
	s_mov_b32 m0, s18
	ds_read_b128 v[178:181], v194 offset:32768
	ds_read_b128 v[182:185], v194 offset:33792
	ds_read_b128 v[186:189], v194 offset:34816
	ds_read_b128 v[196:199], v194 offset:35840
	ds_read_b128 v[200:203], v194 offset:36864
	ds_read_b128 v[204:207], v194 offset:37888
	ds_read_b128 v[208:211], v194 offset:38912
	ds_read_b128 v[212:215], v194 offset:39936
	s_nop 0
	global_load_lds_dwordx4 v1, s[4:5]
	s_mov_b32 m0, s19
	s_nop 0
	global_load_lds_dwordx4 v164, s[4:5]
	s_waitcnt vmcnt(8)
	s_waitcnt lgkmcnt(0)
	s_barrier
	s_setprio 1
	s_waitcnt lgkmcnt(0)
	v_mfma_f32_16x16x32_bf16 v[142:145], v[74:77], v[178:181], v[142:145]
	v_mfma_f32_16x16x32_bf16 v[142:145], v[78:81], v[182:185], v[142:145]
	v_mfma_f32_16x16x32_bf16 v[134:137], v[74:77], v[186:189], v[134:137]
	v_mfma_f32_16x16x32_bf16 v[134:137], v[78:81], v[196:199], v[134:137]
	v_mfma_f32_16x16x32_bf16 v[126:129], v[74:77], v[200:203], v[126:129]
	v_mfma_f32_16x16x32_bf16 v[126:129], v[78:81], v[204:207], v[126:129]
	v_mfma_f32_16x16x32_bf16 v[118:121], v[74:77], v[208:211], v[118:121]
	v_mfma_f32_16x16x32_bf16 v[118:121], v[78:81], v[212:215], v[118:121]
	v_mfma_f32_16x16x32_bf16 v[138:141], v[98:101], v[178:181], v[138:141]
	v_mfma_f32_16x16x32_bf16 v[138:141], v[102:105], v[182:185], v[138:141]
	v_mfma_f32_16x16x32_bf16 v[130:133], v[98:101], v[186:189], v[130:133]
	v_mfma_f32_16x16x32_bf16 v[130:133], v[102:105], v[196:199], v[130:133]
	v_mfma_f32_16x16x32_bf16 v[122:125], v[98:101], v[200:203], v[122:125]
	v_mfma_f32_16x16x32_bf16 v[122:125], v[102:105], v[204:207], v[122:125]
	v_mfma_f32_16x16x32_bf16 v[114:117], v[98:101], v[208:211], v[114:117]
	v_mfma_f32_16x16x32_bf16 v[114:117], v[102:105], v[212:215], v[114:117]
	v_mfma_f32_16x16x32_bf16 v[70:73], v[146:149], v[178:181], v[70:73]
	v_mfma_f32_16x16x32_bf16 v[70:73], v[150:153], v[182:185], v[70:73]
	v_mfma_f32_16x16x32_bf16 v[62:65], v[146:149], v[186:189], v[62:65]
	v_mfma_f32_16x16x32_bf16 v[62:65], v[150:153], v[196:199], v[62:65]
	v_mfma_f32_16x16x32_bf16 v[54:57], v[146:149], v[200:203], v[54:57]
	v_mfma_f32_16x16x32_bf16 v[54:57], v[150:153], v[204:207], v[54:57]
	v_mfma_f32_16x16x32_bf16 v[46:49], v[146:149], v[208:211], v[46:49]
	v_mfma_f32_16x16x32_bf16 v[46:49], v[150:153], v[212:215], v[46:49]
	v_mfma_f32_16x16x32_bf16 v[66:69], v[154:157], v[178:181], v[66:69]
	v_mfma_f32_16x16x32_bf16 v[66:69], v[158:161], v[182:185], v[66:69]
	v_mfma_f32_16x16x32_bf16 v[58:61], v[154:157], v[186:189], v[58:61]
	v_mfma_f32_16x16x32_bf16 v[58:61], v[158:161], v[196:199], v[58:61]
	v_mfma_f32_16x16x32_bf16 v[50:53], v[154:157], v[200:203], v[50:53]
	v_mfma_f32_16x16x32_bf16 v[50:53], v[158:161], v[204:207], v[50:53]
	v_mfma_f32_16x16x32_bf16 v[42:45], v[154:157], v[208:211], v[42:45]
	v_mfma_f32_16x16x32_bf16 v[42:45], v[158:161], v[212:215], v[42:45]
	s_setprio 0
	s_barrier
	s_add_u32 s4, s8, 0x80
	s_addc_u32 s5, s9, 0
	s_add_i32 s10, s38, s15
	ds_read_b128 v[178:181], v194 offset:49152
	ds_read_b128 v[182:185], v194 offset:50176
	ds_read_b128 v[186:189], v194 offset:51200
	ds_read_b128 v[196:199], v194 offset:52224
	ds_read_b128 v[200:203], v194 offset:53248
	ds_read_b128 v[204:207], v194 offset:54272
	ds_read_b128 v[208:211], v194 offset:55296
	ds_read_b128 v[212:215], v194 offset:56320
	s_mov_b32 m0, s10
	s_nop 0
	global_load_lds_dwordx4 v162, s[4:5]
	s_add_i32 m0, s10, 0x2000
	s_nop 0
	global_load_lds_dwordx4 v190, s[4:5]
	s_add_u32 s4, s8, 0x160080
	s_addc_u32 s5, s9, 0
	s_add_i32 s8, s39, s15
	s_mov_b32 m0, s8
	s_nop 0
	global_load_lds_dwordx4 v162, s[4:5]
	s_add_i32 m0, s8, 0x2000
	s_nop 0
	global_load_lds_dwordx4 v190, s[4:5]
	s_mov_b32 m0, s24
	s_nop 0
	global_load_lds_dwordx4 v1, s[6:7]
	s_mov_b32 m0, s25
	s_nop 0
	global_load_lds_dwordx4 v164, s[6:7]
	s_waitcnt vmcnt(8)
	s_waitcnt lgkmcnt(0)
	s_barrier
; #define PG8_MMA(ai, bj, At, Bt) do { __builtin_amdgcn_s_setprio(1); _Pragma("unroll") for (int m = 0; m < 4; ++m) _Pragma("unroll") for (int n = 0; n < 2; ++n) _Pragma("unroll") for (int k = 0; k < 2; ++k) \
;         acc[ai][bj][m][n] = __builtin_amdgcn_mfma_f32_16x16x32_bf16(Bt[n][k], At[m][k], acc[ai][bj][m][n], 0, 0, 0); __builtin_amdgcn_s_setprio(0); } while (0)
; #define PG8_WAIT_V(n) asm volatile("s_waitcnt vmcnt(" #n ")" ::: "memory")
; #define PG8_WAIT_L(n) asm volatile("s_waitcnt lgkmcnt(" #n ")" ::: "memory")
; #define PG8_BAR __builtin_amdgcn_s_barrier()
; #define PG8_SCHED __builtin_amdgcn_sched_barrier(0)
;     __device__ __forceinline__ void operator()(const f32x4 (&acc)[2][2][4][2], const Unit& u, int wr, int wc, int fr, int fq) const {
;         const int row0 = u.pm * BM + wr * 64 + fr, col0 = u.pn * BM + wc * 32 + 8 * fq, b = (u.pm * BM) / rows_per_batch;
;         const float* g = gate + (size_t)b * gate_bstride + col0;
;         float ssq[2][4];
; #pragma unroll
;         for (int ai = 0; ai < 2; ++ai)
; #pragma unroll
;             for (int m = 0; m < 4; ++m) ssq[ai][m] = 0.f;
;         f32x4 gv[2][2], Gv[2][2];
; #pragma unroll
;         for (int bj = 0; bj < 2; ++bj) { gv[bj][0] = *(const f32x4*)(g + bj * HALF); gv[bj][1] = *(const f32x4*)(g + bj * HALF + 4); Gv[bj][0] = (f32x4){0.f, 0.f, 0.f, 0.f}; Gv[bj][1] = (f32x4){0.f, 0.f, 0.f, 0.f};
;             if (Hn) { const float* sc = scnext + (size_t)b * gate_bstride + col0 + bj * HALF;
;                 Gv[bj][0] = *(const f32x4*)(gnext + col0 + bj * HALF) * (1.0f + *(const f32x4*)(sc)); Gv[bj][1] = *(const f32x4*)(gnext + col0 + bj * HALF + 4) * (1.0f + *(const f32x4*)(sc + 4)); } }
; template <class Epi, class Sched, bool ALIGN_EPI = false, bool SP2 = false>
; __device__ __forceinline__ void gemm_phase(PG8_LAS unsigned char* lds, const Gemm g, const Sched& S, const Epi& E) {
;     ...
;             PG8_WAIT_V(8); PG8_WAIT_L(0); PG8_BAR; PG8_MMA(1, 0, At, B0); PG8_MMA(1, 1, At, B1); PG8_BAR; PG8_SCHED;
	s_setprio 1
	s_waitcnt lgkmcnt(0)
	v_mfma_f32_16x16x32_bf16 v[110:113], v[74:77], v[178:181], v[110:113]
	v_mfma_f32_16x16x32_bf16 v[110:113], v[78:81], v[182:185], v[110:113]
	v_mfma_f32_16x16x32_bf16 v[94:97], v[74:77], v[186:189], v[94:97]
	v_mfma_f32_16x16x32_bf16 v[94:97], v[78:81], v[196:199], v[94:97]
	v_mfma_f32_16x16x32_bf16 v[86:89], v[74:77], v[200:203], v[86:89]
	v_mfma_f32_16x16x32_bf16 v[86:89], v[78:81], v[204:207], v[86:89]
	v_mfma_f32_16x16x32_bf16 v[34:37], v[74:77], v[208:211], v[34:37]
	v_mfma_f32_16x16x32_bf16 v[78:81], v[78:81], v[212:215], v[34:37]
	v_mfma_f32_16x16x32_bf16 v[106:109], v[98:101], v[178:181], v[106:109]
	v_mfma_f32_16x16x32_bf16 v[106:109], v[102:105], v[182:185], v[106:109]
	v_mfma_f32_16x16x32_bf16 v[90:93], v[98:101], v[186:189], v[90:93]
	v_mfma_f32_16x16x32_bf16 v[90:93], v[102:105], v[196:199], v[90:93]
	v_mfma_f32_16x16x32_bf16 v[82:85], v[98:101], v[200:203], v[82:85]
	v_mfma_f32_16x16x32_bf16 v[82:85], v[102:105], v[204:207], v[82:85]
	v_mfma_f32_16x16x32_bf16 v[34:37], v[98:101], v[208:211], v[38:41]
	v_mfma_f32_16x16x32_bf16 v[74:77], v[102:105], v[212:215], v[34:37]
	v_mfma_f32_16x16x32_bf16 v[30:33], v[146:149], v[178:181], v[30:33]
	v_mfma_f32_16x16x32_bf16 v[30:33], v[150:153], v[182:185], v[30:33]
	v_mfma_f32_16x16x32_bf16 v[22:25], v[146:149], v[186:189], v[22:25]
	v_mfma_f32_16x16x32_bf16 v[22:25], v[150:153], v[196:199], v[22:25]
	v_mfma_f32_16x16x32_bf16 v[14:17], v[146:149], v[200:203], v[14:17]
	v_mfma_f32_16x16x32_bf16 v[14:17], v[150:153], v[204:207], v[14:17]
	v_mfma_f32_16x16x32_bf16 v[6:9], v[146:149], v[208:211], v[6:9]
	v_mfma_f32_16x16x32_bf16 v[6:9], v[150:153], v[212:215], v[6:9]
	v_mfma_f32_16x16x32_bf16 v[26:29], v[154:157], v[178:181], v[26:29]
	v_mfma_f32_16x16x32_bf16 v[26:29], v[158:161], v[182:185], v[26:29]
	v_mfma_f32_16x16x32_bf16 v[18:21], v[154:157], v[186:189], v[18:21]
	v_mfma_f32_16x16x32_bf16 v[18:21], v[158:161], v[196:199], v[18:21]
	v_mfma_f32_16x16x32_bf16 v[10:13], v[154:157], v[200:203], v[10:13]
	v_mfma_f32_16x16x32_bf16 v[10:13], v[158:161], v[204:207], v[10:13]
	v_mfma_f32_16x16x32_bf16 v[2:5], v[154:157], v[208:211], v[2:5]
	v_mfma_f32_16x16x32_bf16 v[2:5], v[158:161], v[212:215], v[2:5]
	s_setprio 0
	s_barrier
	s_add_i32 s35, s35, 2
	s_add_u32 s31, s31, 0x100
	s_addc_u32 s34, s34, 0
	s_cmpk_gt_u32 s35, 0x55
	s_mov_b64 s[4:5], s[2:3]
	s_cbranch_scc0 .LBB0_707
	s_ashr_i32 s2, s29, 31
	s_lshr_b32 s2, s2, 27
	s_add_i32 s2, s29, s2
	s_ashr_i32 s2, s2, 5
	v_lshl_or_b32 v156, s30, 8, v193
	s_mul_i32 s5, s2, 0xc000
	v_ashrrev_i32_e32 v157, 31, v156
	s_mul_hi_i32 s4, s2, 0xc000
	s_add_u32 s2, s20, s5
	s_addc_u32 s3, s21, s4
	v_lshlrev_b64 v[34:35], 2, v[156:157]
	v_lshl_add_u64 v[38:39], s[2:3], 0, v[34:35]
	global_load_dwordx4 v[98:101], v[38:39], off offset:16
	global_load_dwordx4 v[102:105], v[38:39], off
	s_add_u32 s2, s22, s5
	s_addc_u32 s3, s23, s4
	v_lshl_add_u64 v[148:149], s[2:3], 0, v[34:35]
	v_lshl_add_u64 v[146:147], s[48:49], 0, v[34:35]
	v_mov_b32_e32 v158, 0
	v_cndmask_b32_e64 v34, 0, 1, s[46:47]
	v_cmp_ne_u32_e64 s[2:3], 1, v34
	s_andn2_b64 vcc, exec, s[46:47]
	v_mov_b32_e32 v159, v158
	v_mov_b32_e32 v160, v158
	v_mov_b32_e32 v161, v158
	v_mov_b32_e32 v178, v158
	v_mov_b32_e32 v179, v158
	v_mov_b32_e32 v180, v158
	v_mov_b32_e32 v181, v158
	s_cbranch_vccnz .LBB0_710
	global_load_dwordx4 v[34:37], v[148:149], off
	global_load_dwordx4 v[150:153], v[148:149], off offset:16
	global_load_dwordx4 v[158:161], v[146:147], off
	global_load_dwordx4 v[178:181], v[146:147], off offset:16
	s_waitcnt vmcnt(0)
	v_pk_add_f32 v[36:37], v[36:37], 1.0 op_sel_hi:[1,0]
	v_pk_add_f32 v[34:35], v[34:35], 1.0 op_sel_hi:[1,0]
	v_pk_add_f32 v[40:41], v[152:153], 1.0 op_sel_hi:[1,0]
	v_pk_add_f32 v[150:151], v[150:151], 1.0 op_sel_hi:[1,0]
	v_pk_mul_f32 v[160:161], v[160:161], v[36:37]
	v_pk_mul_f32 v[158:159], v[158:159], v[34:35]
	v_pk_mul_f32 v[180:181], v[180:181], v[40:41]
	v_pk_mul_f32 v[178:179], v[178:179], v[150:151]
